# hand-written residual-add GEMM epilogue in the four latent residual phases (no per-row division or exec-masked pointer select, 4 row chunks of loads in flight)
# speedup vs baseline: 1.0108x; 1.0108x over previous
; template <class Get, class Epi>
; DI void gemm_stream(LAS unsigned char* lds, const int K, const int ld, Get get, Epi epi) {
;     ...
;         if (!has_next) break;
;         ZERO_ACC;
;         cur = nxt; cA = nA; cB = nB; ++ui;
; DI void epi_resid(const Acc& acc, const P& p, int brow, int bcol, int layer, int gch, bool from_input) {
;     ...
;                     *(f32x4*)(xrow(p, r) + c0) = xv[ai][m] + g * acc[ai][bj][m][n];
.LBB0_1234:
.Lresid_latch_wout0:
	s_and_b64 vcc, exec, s[4:5]
	s_mov_b32 s14, s2
	s_mov_b32 s15, s3
	s_mov_b64 s[8:9], s[40:41]
	s_mov_b64 s[6:7], s[38:39]
	s_cbranch_vccnz .LBB0_1495

; #define WAIT_V(n) asm volatile("s_waitcnt vmcnt(" #n ")" ::: "memory")
; #define WAIT_L(n) asm volatile("s_waitcnt lgkmcnt(" #n ")" ::: "memory")
; #define BAR __builtin_amdgcn_s_barrier()
; #define SCHED __builtin_amdgcn_sched_barrier(0)
; template <class Get, class Epi>
; DI void gemm_stream(LAS unsigned char* lds, const int K, const int ld, Get get, Epi epi) {
;     ...
;             LDB(B0, 0, 0); SCHED; LDA(At, 0, 0); STAGE(SAo(1, 1), a1 + hstep);
;             WAIT_L(8); BAR; WAIT_L(0); MMA(0, 0, At, B0); BAR; SCHED;
;             LDB(B1, 0, 1); STAGE(SBo(0, 0), b2);
;             BAR; WAIT_L(0); MMA(0, 1, At, B1); BAR;
;             LDA(At, 0, 1); STAGE(SAo(0, 0), a2);
;             BAR; WAIT_L(0); MMA(1, 0, At, B0); BAR; SCHED;
;             STAGE(SBo(0, 1), b2 + hstep);
;             WAIT_V(6); BAR; MMA(1, 1, At, B1); BAR;
.LBB0_1238:
	ds_read_b128 v[128:131], v198
	ds_read_b128 v[132:135], v198 offset:1024
	ds_read_b128 v[136:139], v198 offset:2048
	ds_read_b128 v[140:143], v198 offset:3072
	s_add_u32 s8, s6, 0x100
	s_addc_u32 s9, s7, 0
	s_cmp_eq_u32 s18, 28
	s_cselect_b32 s13, s39, s9
	s_cselect_b32 s12, s38, s8
	s_cselect_b32 s11, s41, s17
	s_cselect_b32 s10, s40, s16
	s_mov_b32 m0, s74
	v_lshl_add_u64 v[186:187], s[6:7], 0, v[168:169]
	ds_read_b128 v[144:147], v199
	ds_read_b128 v[148:151], v199 offset:1024
	ds_read_b128 v[152:155], v199 offset:2048
	ds_read_b128 v[156:159], v199 offset:3072
	ds_read_b128 v[160:163], v199 offset:4096
	ds_read_b128 v[174:177], v199 offset:5120
	ds_read_b128 v[178:181], v199 offset:6144
	ds_read_b128 v[182:185], v199 offset:7168
	global_load_lds_dwordx4 v[186:187], off
	v_lshl_add_u64 v[186:187], s[6:7], 0, v[170:171]
	s_mov_b32 m0, s75
	s_nop 0
	global_load_lds_dwordx4 v[186:187], off
	s_waitcnt lgkmcnt(8)
	s_barrier
	s_waitcnt lgkmcnt(0)
	v_mfma_f32_16x16x32_bf16 v[124:127], v[128:131], v[144:147], v[124:127]
	v_mfma_f32_16x16x32_bf16 v[92:95], v[136:139], v[144:147], v[92:95]
	v_mfma_f32_16x16x32_bf16 v[120:123], v[128:131], v[152:155], v[120:123]
	v_mfma_f32_16x16x32_bf16 v[88:91], v[136:139], v[152:155], v[88:91]
	v_mfma_f32_16x16x32_bf16 v[116:119], v[128:131], v[160:163], v[116:119]
	v_mfma_f32_16x16x32_bf16 v[84:87], v[136:139], v[160:163], v[84:87]
	v_mfma_f32_16x16x32_bf16 v[112:115], v[128:131], v[178:181], v[112:115]
	v_mfma_f32_16x16x32_bf16 v[80:83], v[136:139], v[178:181], v[80:83]
	v_mfma_f32_16x16x32_bf16 v[124:127], v[132:135], v[148:151], v[124:127]
	v_mfma_f32_16x16x32_bf16 v[92:95], v[140:143], v[148:151], v[92:95]
	v_mfma_f32_16x16x32_bf16 v[120:123], v[132:135], v[156:159], v[120:123]
	v_mfma_f32_16x16x32_bf16 v[88:91], v[140:143], v[156:159], v[88:91]
	v_mfma_f32_16x16x32_bf16 v[116:119], v[132:135], v[174:177], v[116:119]
	v_mfma_f32_16x16x32_bf16 v[84:87], v[140:143], v[174:177], v[84:87]
	v_mfma_f32_16x16x32_bf16 v[112:115], v[132:135], v[182:185], v[112:115]
	v_mfma_f32_16x16x32_bf16 v[80:83], v[140:143], v[182:185], v[80:83]
	s_barrier
	s_mov_b32 m0, s80
	v_lshl_add_u64 v[204:205], s[10:11], 0, v[164:165]
	ds_read_b128 v[186:189], v200
	ds_read_b128 v[190:193], v200 offset:1024
	ds_read_b128 v[194:197], v200 offset:2048
	ds_read_b128 v[208:211], v200 offset:3072
	global_load_lds_dwordx4 v[204:205], off
	v_lshl_add_u64 v[212:213], s[10:11], 0, v[166:167]
	s_mov_b32 m0, s81
	s_nop 0
	global_load_lds_dwordx4 v[212:213], off
	s_barrier
	s_waitcnt lgkmcnt(0)
	v_mfma_f32_16x16x32_bf16 v[60:63], v[186:189], v[144:147], v[60:63]
	v_mfma_f32_16x16x32_bf16 v[28:31], v[194:197], v[144:147], v[28:31]
	v_mfma_f32_16x16x32_bf16 v[56:59], v[186:189], v[152:155], v[56:59]
	v_mfma_f32_16x16x32_bf16 v[24:27], v[194:197], v[152:155], v[24:27]
	v_mfma_f32_16x16x32_bf16 v[52:55], v[186:189], v[160:163], v[52:55]
	v_mfma_f32_16x16x32_bf16 v[20:23], v[194:197], v[160:163], v[20:23]
	v_mfma_f32_16x16x32_bf16 v[48:51], v[186:189], v[178:181], v[48:51]
	v_mfma_f32_16x16x32_bf16 v[16:19], v[194:197], v[178:181], v[16:19]
	v_mfma_f32_16x16x32_bf16 v[60:63], v[190:193], v[148:151], v[60:63]
	v_mfma_f32_16x16x32_bf16 v[28:31], v[208:211], v[148:151], v[28:31]
	v_mfma_f32_16x16x32_bf16 v[56:59], v[190:193], v[156:159], v[56:59]
	v_mfma_f32_16x16x32_bf16 v[24:27], v[208:211], v[156:159], v[24:27]
	v_mfma_f32_16x16x32_bf16 v[52:55], v[190:193], v[174:177], v[52:55]
	v_mfma_f32_16x16x32_bf16 v[20:23], v[208:211], v[174:177], v[20:23]
	v_mfma_f32_16x16x32_bf16 v[48:51], v[190:193], v[182:185], v[48:51]
	v_mfma_f32_16x16x32_bf16 v[16:19], v[208:211], v[182:185], v[16:19]
	s_mov_b32 m0, s21
	v_lshl_add_u64 v[214:215], s[12:13], 0, v[164:165]
	s_barrier
	ds_read_b128 v[144:147], v199 offset:16384
	ds_read_b128 v[148:151], v199 offset:17408
	ds_read_b128 v[152:155], v199 offset:18432
	ds_read_b128 v[156:159], v199 offset:19456
	ds_read_b128 v[160:163], v199 offset:20480
	ds_read_b128 v[174:177], v199 offset:21504
	ds_read_b128 v[178:181], v199 offset:22528
	ds_read_b128 v[182:185], v199 offset:23552
	global_load_lds_dwordx4 v[214:215], off
	v_lshl_add_u64 v[216:217], s[12:13], 0, v[166:167]
	s_mov_b32 m0, s58
	s_nop 0
	global_load_lds_dwordx4 v[216:217], off
	s_barrier
	s_waitcnt lgkmcnt(0)
	v_mfma_f32_16x16x32_bf16 v[108:111], v[128:131], v[144:147], v[108:111]
	v_mfma_f32_16x16x32_bf16 v[76:79], v[136:139], v[144:147], v[76:79]
	v_mfma_f32_16x16x32_bf16 v[104:107], v[128:131], v[152:155], v[104:107]
	v_mfma_f32_16x16x32_bf16 v[72:75], v[136:139], v[152:155], v[72:75]
	v_mfma_f32_16x16x32_bf16 v[100:103], v[128:131], v[160:163], v[100:103]
	v_mfma_f32_16x16x32_bf16 v[68:71], v[136:139], v[160:163], v[68:71]
	v_mfma_f32_16x16x32_bf16 v[96:99], v[128:131], v[178:181], v[96:99]
	v_mfma_f32_16x16x32_bf16 v[64:67], v[136:139], v[178:181], v[64:67]
	v_mfma_f32_16x16x32_bf16 v[108:111], v[132:135], v[148:151], v[108:111]
	v_mfma_f32_16x16x32_bf16 v[76:79], v[140:143], v[148:151], v[76:79]
	v_mfma_f32_16x16x32_bf16 v[104:107], v[132:135], v[156:159], v[104:107]
	v_mfma_f32_16x16x32_bf16 v[72:75], v[140:143], v[156:159], v[72:75]
	v_mfma_f32_16x16x32_bf16 v[100:103], v[132:135], v[174:177], v[100:103]
	v_mfma_f32_16x16x32_bf16 v[68:71], v[140:143], v[174:177], v[68:71]
	v_mfma_f32_16x16x32_bf16 v[96:99], v[132:135], v[182:185], v[96:99]
	v_mfma_f32_16x16x32_bf16 v[64:67], v[140:143], v[182:185], v[64:67]
	s_barrier
	s_add_u32 s6, s10, 0x80000
	s_addc_u32 s7, s11, 0
	s_mov_b32 m0, s82
	v_lshl_add_u64 v[128:129], s[6:7], 0, v[164:165]
	global_load_lds_dwordx4 v[128:129], off
	v_lshl_add_u64 v[128:129], s[6:7], 0, v[166:167]
	s_mov_b32 m0, s83
	s_nop 0
	global_load_lds_dwordx4 v[128:129], off
	s_waitcnt vmcnt(6)
	s_barrier
; #define WAIT_V(n) asm volatile("s_waitcnt vmcnt(" #n ")" ::: "memory")
; #define WAIT_L(n) asm volatile("s_waitcnt lgkmcnt(" #n ")" ::: "memory")
; #define BAR __builtin_amdgcn_s_barrier()
; #define SCHED __builtin_amdgcn_sched_barrier(0)
; template <class Get, class Epi>
; DI void gemm_stream(LAS unsigned char* lds, const int K, const int ld, Get get, Epi epi) {
;     ...
;             LDB(B0, 1, 0); SCHED; LDA(At, 1, 0); STAGE(SAo(0, 1), a2 + hstep);
;             WAIT_L(8); BAR; WAIT_L(0); MMA(0, 0, At, B0); BAR; SCHED;
;             LDB(B1, 1, 1); STAGE(SBo(1, 0), b3);
;             BAR; WAIT_L(0); MMA(0, 1, At, B1); BAR;
;             LDA(At, 1, 1); STAGE(SAo(1, 0), a3);
;             BAR; WAIT_L(0); MMA(1, 0, At, B0); BAR; SCHED;
;             STAGE(SBo(1, 1), b3 + hstep);
;             WAIT_V(6); BAR; MMA(1, 1, At, B1); BAR;
	v_mfma_f32_16x16x32_bf16 v[44:47], v[186:189], v[144:147], v[44:47]
	v_mfma_f32_16x16x32_bf16 v[12:15], v[194:197], v[144:147], v[12:15]
	v_mfma_f32_16x16x32_bf16 v[40:43], v[186:189], v[152:155], v[40:43]
	v_mfma_f32_16x16x32_bf16 v[8:11], v[194:197], v[152:155], v[8:11]
	v_mfma_f32_16x16x32_bf16 v[36:39], v[186:189], v[160:163], v[36:39]
	v_mfma_f32_16x16x32_bf16 v[4:7], v[194:197], v[160:163], v[4:7]
	v_mfma_f32_16x16x32_bf16 v[32:35], v[186:189], v[178:181], v[32:35]
	v_mfma_f32_16x16x32_bf16 v[0:3], v[194:197], v[178:181], v[0:3]
	v_mfma_f32_16x16x32_bf16 v[44:47], v[190:193], v[148:151], v[44:47]
	v_mfma_f32_16x16x32_bf16 v[12:15], v[208:211], v[148:151], v[12:15]
	v_mfma_f32_16x16x32_bf16 v[40:43], v[190:193], v[156:159], v[40:43]
	v_mfma_f32_16x16x32_bf16 v[8:11], v[208:211], v[156:159], v[8:11]
	v_mfma_f32_16x16x32_bf16 v[36:39], v[190:193], v[174:177], v[36:39]
	v_mfma_f32_16x16x32_bf16 v[4:7], v[208:211], v[174:177], v[4:7]
	v_mfma_f32_16x16x32_bf16 v[32:35], v[190:193], v[182:185], v[32:35]
	v_mfma_f32_16x16x32_bf16 v[0:3], v[208:211], v[182:185], v[0:3]
	s_barrier
	ds_read_b128 v[128:131], v201
	ds_read_b128 v[132:135], v201 offset:1024
	ds_read_b128 v[136:139], v201 offset:2048
	ds_read_b128 v[140:143], v201 offset:3072
	s_add_u32 s6, s12, 0x80000
	s_addc_u32 s7, s13, 0
	s_mov_b32 m0, s59
	v_lshl_add_u64 v[186:187], s[6:7], 0, v[164:165]
	ds_read_b128 v[144:147], v199 offset:32768
	ds_read_b128 v[148:151], v199 offset:33792
	ds_read_b128 v[152:155], v199 offset:34816
	ds_read_b128 v[156:159], v199 offset:35840
	ds_read_b128 v[160:163], v199 offset:36864
	ds_read_b128 v[174:177], v199 offset:37888
	ds_read_b128 v[178:181], v199 offset:38912
	ds_read_b128 v[182:185], v199 offset:39936
	global_load_lds_dwordx4 v[186:187], off
	v_lshl_add_u64 v[186:187], s[6:7], 0, v[166:167]
	s_mov_b32 m0, s60
	s_nop 0
	global_load_lds_dwordx4 v[186:187], off
	s_waitcnt lgkmcnt(8)
	s_barrier
	s_waitcnt lgkmcnt(0)
	v_mfma_f32_16x16x32_bf16 v[124:127], v[128:131], v[144:147], v[124:127]
	v_mfma_f32_16x16x32_bf16 v[92:95], v[136:139], v[144:147], v[92:95]
	v_mfma_f32_16x16x32_bf16 v[120:123], v[128:131], v[152:155], v[120:123]
	v_mfma_f32_16x16x32_bf16 v[88:91], v[136:139], v[152:155], v[88:91]
	v_mfma_f32_16x16x32_bf16 v[116:119], v[128:131], v[160:163], v[116:119]
	v_mfma_f32_16x16x32_bf16 v[84:87], v[136:139], v[160:163], v[84:87]
	v_mfma_f32_16x16x32_bf16 v[112:115], v[128:131], v[178:181], v[112:115]
	v_mfma_f32_16x16x32_bf16 v[80:83], v[136:139], v[178:181], v[80:83]
	v_mfma_f32_16x16x32_bf16 v[124:127], v[132:135], v[148:151], v[124:127]
	v_mfma_f32_16x16x32_bf16 v[92:95], v[140:143], v[148:151], v[92:95]
	v_mfma_f32_16x16x32_bf16 v[120:123], v[132:135], v[156:159], v[120:123]
	v_mfma_f32_16x16x32_bf16 v[88:91], v[140:143], v[156:159], v[88:91]
	v_mfma_f32_16x16x32_bf16 v[116:119], v[132:135], v[174:177], v[116:119]
	v_mfma_f32_16x16x32_bf16 v[84:87], v[140:143], v[174:177], v[84:87]
	v_mfma_f32_16x16x32_bf16 v[112:115], v[132:135], v[182:185], v[112:115]
	v_mfma_f32_16x16x32_bf16 v[80:83], v[140:143], v[182:185], v[80:83]
	s_barrier
	s_mov_b32 m0, s85
	v_lshl_add_u64 v[204:205], v[204:205], 0, s[0:1]
	ds_read_b128 v[186:189], v202
	ds_read_b128 v[190:193], v202 offset:1024
	ds_read_b128 v[194:197], v202 offset:2048
	ds_read_b128 v[208:211], v202 offset:3072
	global_load_lds_dwordx4 v[204:205], off
	v_lshl_add_u64 v[204:205], v[212:213], 0, s[0:1]
	s_mov_b32 m0, s96
	s_nop 0
	global_load_lds_dwordx4 v[204:205], off
	s_barrier
	s_waitcnt lgkmcnt(0)
	v_mfma_f32_16x16x32_bf16 v[60:63], v[186:189], v[144:147], v[60:63]
	v_mfma_f32_16x16x32_bf16 v[28:31], v[194:197], v[144:147], v[28:31]
	v_mfma_f32_16x16x32_bf16 v[56:59], v[186:189], v[152:155], v[56:59]
	v_mfma_f32_16x16x32_bf16 v[24:27], v[194:197], v[152:155], v[24:27]
	v_mfma_f32_16x16x32_bf16 v[52:55], v[186:189], v[160:163], v[52:55]
	v_mfma_f32_16x16x32_bf16 v[20:23], v[194:197], v[160:163], v[20:23]
	v_mfma_f32_16x16x32_bf16 v[48:51], v[186:189], v[178:181], v[48:51]
	v_mfma_f32_16x16x32_bf16 v[16:19], v[194:197], v[178:181], v[16:19]
	v_mfma_f32_16x16x32_bf16 v[60:63], v[190:193], v[148:151], v[60:63]
	v_mfma_f32_16x16x32_bf16 v[28:31], v[208:211], v[148:151], v[28:31]
	v_mfma_f32_16x16x32_bf16 v[56:59], v[190:193], v[156:159], v[56:59]
	v_mfma_f32_16x16x32_bf16 v[24:27], v[208:211], v[156:159], v[24:27]
	v_mfma_f32_16x16x32_bf16 v[52:55], v[190:193], v[174:177], v[52:55]
	v_mfma_f32_16x16x32_bf16 v[20:23], v[208:211], v[174:177], v[20:23]
	v_mfma_f32_16x16x32_bf16 v[48:51], v[190:193], v[182:185], v[48:51]
	v_mfma_f32_16x16x32_bf16 v[16:19], v[208:211], v[182:185], v[16:19]
	s_mov_b32 m0, s61
	v_lshl_add_u64 v[204:205], v[214:215], 0, s[0:1]
	s_barrier
	ds_read_b128 v[144:147], v199 offset:49152
	ds_read_b128 v[148:151], v199 offset:50176
	ds_read_b128 v[152:155], v199 offset:51200
	ds_read_b128 v[156:159], v199 offset:52224
	ds_read_b128 v[160:163], v199 offset:53248
	ds_read_b128 v[174:177], v199 offset:54272
	ds_read_b128 v[178:181], v199 offset:55296
	ds_read_b128 v[182:185], v199 offset:56320
	global_load_lds_dwordx4 v[204:205], off
	v_lshl_add_u64 v[204:205], v[216:217], 0, s[0:1]
	s_mov_b32 m0, s62
	s_nop 0
	global_load_lds_dwordx4 v[204:205], off
	s_barrier
; #define WAIT_V(n) asm volatile("s_waitcnt vmcnt(" #n ")" ::: "memory")
; #define WAIT_L(n) asm volatile("s_waitcnt lgkmcnt(" #n ")" ::: "memory")
; #define BAR __builtin_amdgcn_s_barrier()
; #define SCHED __builtin_amdgcn_sched_barrier(0)
; template <class Get, class Epi>
; DI void gemm_stream(LAS unsigned char* lds, const int K, const int ld, Get get, Epi epi) {
;     ...
;             BAR; WAIT_L(0); MMA(1, 0, At, B0); BAR; SCHED;
;             STAGE(SBo(1, 1), b3 + hstep);
;             WAIT_V(6); BAR; MMA(1, 1, At, B1); BAR;
;         }
; DI void epi_resid(const Acc& acc, const P& p, int brow, int bcol, int layer, int gch, bool from_input) {
;     ...
;     for (int bj = 0; bj < 2; ++bj)
; #pragma unroll
;         for (int n = 0; n < 2; ++n) {
;             const int c0 = bcol + bj * 128 + wc * 32 + n * 16 + fq * 4;
;             const f32x4 g = *(const f32x4*)(gate + c0);
;             f32x4 xv[2][4];
; #pragma unroll
;             for (int ai = 0; ai < 2; ++ai)
; #pragma unroll
;                 for (int m = 0; m < 4; ++m) {
;                     const int r = brow + ai * 128 + wr * 64 + m * 16 + fr;
;                     const float* sp = (from_input ? inrow(p, r) : xrow(p, r)) + c0;
;                     xv[ai][m] = *(const f32x4*)sp;
;                 }
;             __builtin_amdgcn_sched_barrier(0);
; #pragma unroll
;             for (int ai = 0; ai < 2; ++ai)
; #pragma unroll
;                 for (int m = 0; m < 4; ++m) {
;                     const int r = brow + ai * 128 + wr * 64 + m * 16 + fr;
;                     *(f32x4*)(xrow(p, r) + c0) = xv[ai][m] + g * acc[ai][bj][m][n];
;                 }
	s_waitcnt lgkmcnt(0)
	v_mfma_f32_16x16x32_bf16 v[108:111], v[128:131], v[144:147], v[108:111]
	v_mfma_f32_16x16x32_bf16 v[76:79], v[136:139], v[144:147], v[76:79]
	v_mfma_f32_16x16x32_bf16 v[104:107], v[128:131], v[152:155], v[104:107]
	v_mfma_f32_16x16x32_bf16 v[72:75], v[136:139], v[152:155], v[72:75]
	v_mfma_f32_16x16x32_bf16 v[100:103], v[128:131], v[160:163], v[100:103]
	v_mfma_f32_16x16x32_bf16 v[68:71], v[136:139], v[160:163], v[68:71]
	v_mfma_f32_16x16x32_bf16 v[96:99], v[128:131], v[178:181], v[96:99]
	v_mfma_f32_16x16x32_bf16 v[64:67], v[136:139], v[178:181], v[64:67]
	v_mfma_f32_16x16x32_bf16 v[108:111], v[132:135], v[148:151], v[108:111]
	v_mfma_f32_16x16x32_bf16 v[76:79], v[140:143], v[148:151], v[76:79]
	v_mfma_f32_16x16x32_bf16 v[104:107], v[132:135], v[156:159], v[104:107]
	v_mfma_f32_16x16x32_bf16 v[72:75], v[140:143], v[156:159], v[72:75]
	v_mfma_f32_16x16x32_bf16 v[100:103], v[132:135], v[174:177], v[100:103]
	v_mfma_f32_16x16x32_bf16 v[68:71], v[140:143], v[174:177], v[68:71]
	v_mfma_f32_16x16x32_bf16 v[96:99], v[132:135], v[182:185], v[96:99]
	v_mfma_f32_16x16x32_bf16 v[64:67], v[140:143], v[182:185], v[64:67]
	s_barrier
	s_add_u32 s6, s10, 0x80080
	s_addc_u32 s7, s11, 0
	s_mov_b32 m0, s97
	v_lshl_add_u64 v[128:129], s[6:7], 0, v[164:165]
	global_load_lds_dwordx4 v[128:129], off
	v_lshl_add_u64 v[128:129], s[6:7], 0, v[166:167]
	s_add_i32 m0, s97, 0x2000
	s_nop 0
	global_load_lds_dwordx4 v[128:129], off
	s_waitcnt vmcnt(6)
	s_barrier
	v_mfma_f32_16x16x32_bf16 v[44:47], v[186:189], v[144:147], v[44:47]
	v_mfma_f32_16x16x32_bf16 v[12:15], v[194:197], v[144:147], v[12:15]
	v_mfma_f32_16x16x32_bf16 v[40:43], v[186:189], v[152:155], v[40:43]
	v_mfma_f32_16x16x32_bf16 v[8:11], v[194:197], v[152:155], v[8:11]
	v_mfma_f32_16x16x32_bf16 v[36:39], v[186:189], v[160:163], v[36:39]
	v_mfma_f32_16x16x32_bf16 v[4:7], v[194:197], v[160:163], v[4:7]
	v_mfma_f32_16x16x32_bf16 v[32:35], v[186:189], v[178:181], v[32:35]
	v_mfma_f32_16x16x32_bf16 v[0:3], v[194:197], v[178:181], v[0:3]
	v_mfma_f32_16x16x32_bf16 v[44:47], v[190:193], v[148:151], v[44:47]
	v_mfma_f32_16x16x32_bf16 v[12:15], v[208:211], v[148:151], v[12:15]
	v_mfma_f32_16x16x32_bf16 v[40:43], v[190:193], v[156:159], v[40:43]
	v_mfma_f32_16x16x32_bf16 v[8:11], v[208:211], v[156:159], v[8:11]
	v_mfma_f32_16x16x32_bf16 v[36:39], v[190:193], v[174:177], v[36:39]
	v_mfma_f32_16x16x32_bf16 v[4:7], v[208:211], v[174:177], v[4:7]
	v_mfma_f32_16x16x32_bf16 v[32:35], v[190:193], v[182:185], v[32:35]
	v_mfma_f32_16x16x32_bf16 v[0:3], v[208:211], v[182:185], v[0:3]
	s_add_i32 s18, s18, 2
	s_add_u32 s16, s16, 0x100
	s_addc_u32 s17, s17, 0
	s_cmp_gt_u32 s18, 29
	s_mov_b64 s[6:7], s[8:9]
	s_barrier
	s_cbranch_scc0 .LBB0_1238
	s_lshl_b32 s12, s15, 21
	s_lshl_b32 s13, s14, 10
	s_lshr_b32 s16, s15, 4
	s_add_u32 s12, s12, s13
	s_mul_i32 s16, s16, 6
	s_add_i32 s16, s16, 2
	s_lshl_b32 s16, s16, 13
	s_add_u32 s16, s16, s13
	s_add_u32 s10, s26, s16
	s_addc_u32 s11, s27, 0
	s_add_u32 s8, s52, s12
	s_addc_u32 s9, s53, 0
	s_add_u32 s6, s24, s12
	s_addc_u32 s7, s25, 0
	v_lshrrev_b32_e32 v224, 6, v206
	v_and_b32_e32 v225, 3, v224
	v_lshrrev_b32_e32 v224, 2, v224
	v_and_b32_e32 v205, 15, v206
	v_bfe_u32 v226, v206, 4, 2
	v_lshl_add_u32 v225, v225, 3, v226
	v_lshl_add_u32 v224, v224, 6, v205
	v_lshlrev_b32_e32 v205, 4, v225
	v_lshl_add_u32 v203, v224, 13, v205
	v_mov_b32_e32 v204, v203
	global_load_dwordx4 v[128:131], v205, s[10:11] offset:0
	global_load_dwordx4 v[132:135], v205, s[10:11] offset:64
	global_load_dwordx4 v[136:139], v205, s[10:11] offset:512
	global_load_dwordx4 v[140:143], v205, s[10:11] offset:576
	global_load_dwordx4 v[144:147], v203, s[8:9] offset:0
	global_load_dwordx4 v[148:151], v203, s[8:9] offset:64
	global_load_dwordx4 v[152:155], v203, s[8:9] offset:512
	global_load_dwordx4 v[156:159], v203, s[8:9] offset:576
	v_add_u32_e32 v203, 0x20000, v203
	global_load_dwordx4 v[160:163], v203, s[8:9] offset:0
	global_load_dwordx4 v[174:177], v203, s[8:9] offset:64
	global_load_dwordx4 v[178:181], v203, s[8:9] offset:512
	global_load_dwordx4 v[182:185], v203, s[8:9] offset:576
	v_add_u32_e32 v203, 0x20000, v203
	global_load_dwordx4 v[186:189], v203, s[8:9] offset:0
	global_load_dwordx4 v[190:193], v203, s[8:9] offset:64
	global_load_dwordx4 v[194:197], v203, s[8:9] offset:512
	global_load_dwordx4 v[208:211], v203, s[8:9] offset:576
	v_add_u32_e32 v203, 0x20000, v203
	global_load_dwordx4 v[212:215], v203, s[8:9] offset:0
	global_load_dwordx4 v[216:219], v203, s[8:9] offset:64
	global_load_dwordx4 v[220:223], v203, s[8:9] offset:512
	global_load_dwordx4 v[224:227], v203, s[8:9] offset:576
	v_add_u32_e32 v203, 0xa0000, v203
	s_waitcnt vmcnt(12)
	v_pk_fma_f32 v[124:125], v[124:125], v[128:129], v[144:145]
	v_pk_fma_f32 v[126:127], v[126:127], v[130:131], v[146:147]
	v_pk_fma_f32 v[92:93], v[92:93], v[132:133], v[148:149]
	v_pk_fma_f32 v[94:95], v[94:95], v[134:135], v[150:151]
	v_pk_fma_f32 v[60:61], v[60:61], v[136:137], v[152:153]
	v_pk_fma_f32 v[62:63], v[62:63], v[138:139], v[154:155]
	v_pk_fma_f32 v[28:29], v[28:29], v[140:141], v[156:157]
	v_pk_fma_f32 v[30:31], v[30:31], v[142:143], v[158:159]
	global_store_dwordx4 v204, v[124:127], s[6:7] offset:0
	global_store_dwordx4 v204, v[92:95], s[6:7] offset:64
	global_store_dwordx4 v204, v[60:63], s[6:7] offset:512
	global_store_dwordx4 v204, v[28:31], s[6:7] offset:576
	v_add_u32_e32 v204, 0x20000, v204
	global_load_dwordx4 v[144:147], v203, s[8:9] offset:0
	global_load_dwordx4 v[148:151], v203, s[8:9] offset:64
	global_load_dwordx4 v[152:155], v203, s[8:9] offset:512
	global_load_dwordx4 v[156:159], v203, s[8:9] offset:576
	v_add_u32_e32 v203, 0x20000, v203
	s_waitcnt vmcnt(16)
; DI void epi_resid(const Acc& acc, const P& p, int brow, int bcol, int layer, int gch, bool from_input) {
;     ...
; #pragma unroll
;             for (int ai = 0; ai < 2; ++ai)
; #pragma unroll
;                 for (int m = 0; m < 4; ++m) {
;                     const int r = brow + ai * 128 + wr * 64 + m * 16 + fr;
;                     *(f32x4*)(xrow(p, r) + c0) = xv[ai][m] + g * acc[ai][bj][m][n];
;                 }
	v_pk_fma_f32 v[120:121], v[120:121], v[128:129], v[160:161]
	v_pk_fma_f32 v[122:123], v[122:123], v[130:131], v[162:163]
	v_pk_fma_f32 v[88:89], v[88:89], v[132:133], v[174:175]
	v_pk_fma_f32 v[90:91], v[90:91], v[134:135], v[176:177]
	v_pk_fma_f32 v[56:57], v[56:57], v[136:137], v[178:179]
	v_pk_fma_f32 v[58:59], v[58:59], v[138:139], v[180:181]
	v_pk_fma_f32 v[24:25], v[24:25], v[140:141], v[182:183]
	v_pk_fma_f32 v[26:27], v[26:27], v[142:143], v[184:185]
	global_store_dwordx4 v204, v[120:123], s[6:7] offset:0
	global_store_dwordx4 v204, v[88:91], s[6:7] offset:64
	global_store_dwordx4 v204, v[56:59], s[6:7] offset:512
	global_store_dwordx4 v204, v[24:27], s[6:7] offset:576
	v_add_u32_e32 v204, 0x20000, v204
	global_load_dwordx4 v[160:163], v203, s[8:9] offset:0
	global_load_dwordx4 v[174:177], v203, s[8:9] offset:64
	global_load_dwordx4 v[178:181], v203, s[8:9] offset:512
	global_load_dwordx4 v[182:185], v203, s[8:9] offset:576
	v_add_u32_e32 v203, 0x20000, v203
	s_waitcnt vmcnt(20)
	v_pk_fma_f32 v[116:117], v[116:117], v[128:129], v[186:187]
	v_pk_fma_f32 v[118:119], v[118:119], v[130:131], v[188:189]
	v_pk_fma_f32 v[84:85], v[84:85], v[132:133], v[190:191]
	v_pk_fma_f32 v[86:87], v[86:87], v[134:135], v[192:193]
	v_pk_fma_f32 v[52:53], v[52:53], v[136:137], v[194:195]
	v_pk_fma_f32 v[54:55], v[54:55], v[138:139], v[196:197]
	v_pk_fma_f32 v[20:21], v[20:21], v[140:141], v[208:209]
	v_pk_fma_f32 v[22:23], v[22:23], v[142:143], v[210:211]
	global_store_dwordx4 v204, v[116:119], s[6:7] offset:0
	global_store_dwordx4 v204, v[84:87], s[6:7] offset:64
	global_store_dwordx4 v204, v[52:55], s[6:7] offset:512
	global_store_dwordx4 v204, v[20:23], s[6:7] offset:576
	v_add_u32_e32 v204, 0x20000, v204
	global_load_dwordx4 v[186:189], v203, s[8:9] offset:0
	global_load_dwordx4 v[190:193], v203, s[8:9] offset:64
	global_load_dwordx4 v[194:197], v203, s[8:9] offset:512
	global_load_dwordx4 v[208:211], v203, s[8:9] offset:576
	v_add_u32_e32 v203, 0x20000, v203
	s_waitcnt vmcnt(24)
	v_pk_fma_f32 v[112:113], v[112:113], v[128:129], v[212:213]
	v_pk_fma_f32 v[114:115], v[114:115], v[130:131], v[214:215]
	v_pk_fma_f32 v[80:81], v[80:81], v[132:133], v[216:217]
	v_pk_fma_f32 v[82:83], v[82:83], v[134:135], v[218:219]
	v_pk_fma_f32 v[48:49], v[48:49], v[136:137], v[220:221]
	v_pk_fma_f32 v[50:51], v[50:51], v[138:139], v[222:223]
	v_pk_fma_f32 v[16:17], v[16:17], v[140:141], v[224:225]
	v_pk_fma_f32 v[18:19], v[18:19], v[142:143], v[226:227]
	global_store_dwordx4 v204, v[112:115], s[6:7] offset:0
	global_store_dwordx4 v204, v[80:83], s[6:7] offset:64
	global_store_dwordx4 v204, v[48:51], s[6:7] offset:512
	global_store_dwordx4 v204, v[16:19], s[6:7] offset:576
	v_add_u32_e32 v204, 0xa0000, v204
	global_load_dwordx4 v[212:215], v203, s[8:9] offset:0
	global_load_dwordx4 v[216:219], v203, s[8:9] offset:64
	global_load_dwordx4 v[220:223], v203, s[8:9] offset:512
	global_load_dwordx4 v[224:227], v203, s[8:9] offset:576
	s_waitcnt vmcnt(24)
	v_pk_fma_f32 v[108:109], v[108:109], v[128:129], v[144:145]
	v_pk_fma_f32 v[110:111], v[110:111], v[130:131], v[146:147]
	v_pk_fma_f32 v[76:77], v[76:77], v[132:133], v[148:149]
	v_pk_fma_f32 v[78:79], v[78:79], v[134:135], v[150:151]
	v_pk_fma_f32 v[44:45], v[44:45], v[136:137], v[152:153]
	v_pk_fma_f32 v[46:47], v[46:47], v[138:139], v[154:155]
	v_pk_fma_f32 v[12:13], v[12:13], v[140:141], v[156:157]
	v_pk_fma_f32 v[14:15], v[14:15], v[142:143], v[158:159]
	global_store_dwordx4 v204, v[108:111], s[6:7] offset:0
	global_store_dwordx4 v204, v[76:79], s[6:7] offset:64
	global_store_dwordx4 v204, v[44:47], s[6:7] offset:512
	global_store_dwordx4 v204, v[12:15], s[6:7] offset:576
	v_add_u32_e32 v204, 0x20000, v204
	s_waitcnt vmcnt(20)
	v_pk_fma_f32 v[104:105], v[104:105], v[128:129], v[160:161]
	v_pk_fma_f32 v[106:107], v[106:107], v[130:131], v[162:163]
	v_pk_fma_f32 v[72:73], v[72:73], v[132:133], v[174:175]
	v_pk_fma_f32 v[74:75], v[74:75], v[134:135], v[176:177]
	v_pk_fma_f32 v[40:41], v[40:41], v[136:137], v[178:179]
	v_pk_fma_f32 v[42:43], v[42:43], v[138:139], v[180:181]
	v_pk_fma_f32 v[8:9], v[8:9], v[140:141], v[182:183]
	v_pk_fma_f32 v[10:11], v[10:11], v[142:143], v[184:185]
	global_store_dwordx4 v204, v[104:107], s[6:7] offset:0
	global_store_dwordx4 v204, v[72:75], s[6:7] offset:64
	global_store_dwordx4 v204, v[40:43], s[6:7] offset:512
	global_store_dwordx4 v204, v[8:11], s[6:7] offset:576
	v_add_u32_e32 v204, 0x20000, v204
	s_waitcnt vmcnt(16)
	v_pk_fma_f32 v[100:101], v[100:101], v[128:129], v[186:187]
	v_pk_fma_f32 v[102:103], v[102:103], v[130:131], v[188:189]
	v_pk_fma_f32 v[68:69], v[68:69], v[132:133], v[190:191]
	v_pk_fma_f32 v[70:71], v[70:71], v[134:135], v[192:193]
	v_pk_fma_f32 v[36:37], v[36:37], v[136:137], v[194:195]
	v_pk_fma_f32 v[38:39], v[38:39], v[138:139], v[196:197]
	v_pk_fma_f32 v[4:5], v[4:5], v[140:141], v[208:209]
	v_pk_fma_f32 v[6:7], v[6:7], v[142:143], v[210:211]
	global_store_dwordx4 v204, v[100:103], s[6:7] offset:0
	global_store_dwordx4 v204, v[68:71], s[6:7] offset:64
	global_store_dwordx4 v204, v[36:39], s[6:7] offset:512
	global_store_dwordx4 v204, v[4:7], s[6:7] offset:576
	v_add_u32_e32 v204, 0x20000, v204
	s_waitcnt vmcnt(12)
	v_pk_fma_f32 v[96:97], v[96:97], v[128:129], v[212:213]
	v_pk_fma_f32 v[98:99], v[98:99], v[130:131], v[214:215]
	v_pk_fma_f32 v[64:65], v[64:65], v[132:133], v[216:217]
	v_pk_fma_f32 v[66:67], v[66:67], v[134:135], v[218:219]
	v_pk_fma_f32 v[32:33], v[32:33], v[136:137], v[220:221]
	v_pk_fma_f32 v[34:35], v[34:35], v[138:139], v[222:223]
	v_pk_fma_f32 v[0:1], v[0:1], v[140:141], v[224:225]
	v_pk_fma_f32 v[2:3], v[2:3], v[142:143], v[226:227]
	global_store_dwordx4 v204, v[96:99], s[6:7] offset:0
	global_store_dwordx4 v204, v[64:67], s[6:7] offset:64
	global_store_dwordx4 v204, v[32:35], s[6:7] offset:512
	global_store_dwordx4 v204, v[0:3], s[6:7] offset:576
	s_branch .Lresid_latch_wout0

; template <class Get, class Epi>
; DI void gemm_stream(LAS unsigned char* lds, const int K, const int ld, Get get, Epi epi) {
;     ...
;         if (!has_next) break;
;         ZERO_ACC;
;         cur = nxt; cA = nA; cB = nB; ++ui;
; DI void epi_resid(const Acc& acc, const P& p, int brow, int bcol, int layer, int gch, bool from_input) {
;     ...
;                     *(f32x4*)(xrow(p, r) + c0) = xv[ai][m] + g * acc[ai][bj][m][n];
.LBB0_1693:
.Lresid_latch_ffndL0:
	s_and_b64 vcc, exec, s[4:5]
	s_mov_b32 s2, s79
	s_mov_b32 s3, s82
	s_mov_b64 s[8:9], s[40:41]
	s_mov_b64 s[6:7], s[38:39]
	s_cbranch_vccnz .LBB0_1954

; #define WAIT_V(n) asm volatile("s_waitcnt vmcnt(" #n ")" ::: "memory")
; #define WAIT_L(n) asm volatile("s_waitcnt lgkmcnt(" #n ")" ::: "memory")
; #define BAR __builtin_amdgcn_s_barrier()
; #define SCHED __builtin_amdgcn_sched_barrier(0)
; template <class Get, class Epi>
; DI void gemm_stream(LAS unsigned char* lds, const int K, const int ld, Get get, Epi epi) {
;     ...
;             LDB(B0, 0, 0); SCHED; LDA(At, 0, 0); STAGE(SAo(1, 1), a1 + hstep);
;             WAIT_L(8); BAR; WAIT_L(0); MMA(0, 0, At, B0); BAR; SCHED;
;             LDB(B1, 0, 1); STAGE(SBo(0, 0), b2);
;             BAR; WAIT_L(0); MMA(0, 1, At, B1); BAR;
;             LDA(At, 0, 1); STAGE(SAo(0, 0), a2);
;             BAR; WAIT_L(0); MMA(1, 0, At, B0); BAR; SCHED;
;             STAGE(SBo(0, 1), b2 + hstep);
;             WAIT_V(6); BAR; MMA(1, 1, At, B1); BAR;
.LBB0_1697:
	ds_read_b128 v[128:131], v199
	ds_read_b128 v[132:135], v199 offset:1024
	ds_read_b128 v[136:139], v199 offset:2048
	ds_read_b128 v[140:143], v199 offset:3072
	s_add_u32 s8, s6, 0x100
	s_addc_u32 s9, s7, 0
	s_cmpk_eq_i32 s16, 0x54
	s_cselect_b32 s13, s39, s9
	s_cselect_b32 s12, s38, s8
	s_cselect_b32 s11, s41, s15
	s_cselect_b32 s10, s40, s14
	s_mov_b32 m0, s63
	v_lshl_add_u64 v[186:187], s[6:7], 0, v[168:169]
	ds_read_b128 v[144:147], v200
	ds_read_b128 v[148:151], v200 offset:1024
	ds_read_b128 v[152:155], v200 offset:2048
	ds_read_b128 v[156:159], v200 offset:3072
	ds_read_b128 v[160:163], v200 offset:4096
	ds_read_b128 v[174:177], v200 offset:5120
	ds_read_b128 v[178:181], v200 offset:6144
	ds_read_b128 v[182:185], v200 offset:7168
	global_load_lds_dwordx4 v[186:187], off
	v_lshl_add_u64 v[186:187], s[6:7], 0, v[170:171]
	s_mov_b32 m0, s74
	s_nop 0
	global_load_lds_dwordx4 v[186:187], off
	s_waitcnt lgkmcnt(8)
	s_barrier
	s_waitcnt lgkmcnt(0)
	v_mfma_f32_16x16x32_bf16 v[124:127], v[128:131], v[144:147], v[124:127]
	v_mfma_f32_16x16x32_bf16 v[92:95], v[136:139], v[144:147], v[92:95]
	v_mfma_f32_16x16x32_bf16 v[120:123], v[128:131], v[152:155], v[120:123]
	v_mfma_f32_16x16x32_bf16 v[88:91], v[136:139], v[152:155], v[88:91]
	v_mfma_f32_16x16x32_bf16 v[116:119], v[128:131], v[160:163], v[116:119]
	v_mfma_f32_16x16x32_bf16 v[84:87], v[136:139], v[160:163], v[84:87]
	v_mfma_f32_16x16x32_bf16 v[112:115], v[128:131], v[178:181], v[112:115]
	v_mfma_f32_16x16x32_bf16 v[80:83], v[136:139], v[178:181], v[80:83]
	v_mfma_f32_16x16x32_bf16 v[124:127], v[132:135], v[148:151], v[124:127]
	v_mfma_f32_16x16x32_bf16 v[92:95], v[140:143], v[148:151], v[92:95]
	v_mfma_f32_16x16x32_bf16 v[120:123], v[132:135], v[156:159], v[120:123]
	v_mfma_f32_16x16x32_bf16 v[88:91], v[140:143], v[156:159], v[88:91]
	v_mfma_f32_16x16x32_bf16 v[116:119], v[132:135], v[174:177], v[116:119]
	v_mfma_f32_16x16x32_bf16 v[84:87], v[140:143], v[174:177], v[84:87]
	v_mfma_f32_16x16x32_bf16 v[112:115], v[132:135], v[182:185], v[112:115]
	v_mfma_f32_16x16x32_bf16 v[80:83], v[140:143], v[182:185], v[80:83]
	s_barrier
	s_mov_b32 m0, s75
	v_lshl_add_u64 v[208:209], s[10:11], 0, v[164:165]
	ds_read_b128 v[186:189], v201
	ds_read_b128 v[190:193], v201 offset:1024
	ds_read_b128 v[194:197], v201 offset:2048
	ds_read_b128 v[202:205], v201 offset:3072
	global_load_lds_dwordx4 v[208:209], off
	v_lshl_add_u64 v[210:211], s[10:11], 0, v[166:167]
	s_mov_b32 m0, s76
	s_nop 0
	global_load_lds_dwordx4 v[210:211], off
	s_barrier
	s_waitcnt lgkmcnt(0)
	v_mfma_f32_16x16x32_bf16 v[60:63], v[186:189], v[144:147], v[60:63]
	v_mfma_f32_16x16x32_bf16 v[28:31], v[194:197], v[144:147], v[28:31]
	v_mfma_f32_16x16x32_bf16 v[56:59], v[186:189], v[152:155], v[56:59]
	v_mfma_f32_16x16x32_bf16 v[24:27], v[194:197], v[152:155], v[24:27]
	v_mfma_f32_16x16x32_bf16 v[52:55], v[186:189], v[160:163], v[52:55]
	v_mfma_f32_16x16x32_bf16 v[20:23], v[194:197], v[160:163], v[20:23]
	v_mfma_f32_16x16x32_bf16 v[48:51], v[186:189], v[178:181], v[48:51]
	v_mfma_f32_16x16x32_bf16 v[16:19], v[194:197], v[178:181], v[16:19]
	v_mfma_f32_16x16x32_bf16 v[60:63], v[190:193], v[148:151], v[60:63]
	v_mfma_f32_16x16x32_bf16 v[28:31], v[202:205], v[148:151], v[28:31]
	v_mfma_f32_16x16x32_bf16 v[56:59], v[190:193], v[156:159], v[56:59]
	v_mfma_f32_16x16x32_bf16 v[24:27], v[202:205], v[156:159], v[24:27]
	v_mfma_f32_16x16x32_bf16 v[52:55], v[190:193], v[174:177], v[52:55]
	v_mfma_f32_16x16x32_bf16 v[20:23], v[202:205], v[174:177], v[20:23]
	v_mfma_f32_16x16x32_bf16 v[48:51], v[190:193], v[182:185], v[48:51]
	v_mfma_f32_16x16x32_bf16 v[16:19], v[202:205], v[182:185], v[16:19]
	s_mov_b32 m0, s23
	v_lshl_add_u64 v[212:213], s[12:13], 0, v[164:165]
	s_barrier
	ds_read_b128 v[144:147], v200 offset:16384
	ds_read_b128 v[148:151], v200 offset:17408
	ds_read_b128 v[152:155], v200 offset:18432
	ds_read_b128 v[156:159], v200 offset:19456
	ds_read_b128 v[160:163], v200 offset:20480
	ds_read_b128 v[174:177], v200 offset:21504
	ds_read_b128 v[178:181], v200 offset:22528
	ds_read_b128 v[182:185], v200 offset:23552
	global_load_lds_dwordx4 v[212:213], off
	v_lshl_add_u64 v[214:215], s[12:13], 0, v[166:167]
	s_mov_b32 m0, s35
	s_nop 0
	global_load_lds_dwordx4 v[214:215], off
	s_barrier
	s_waitcnt lgkmcnt(0)
	v_mfma_f32_16x16x32_bf16 v[108:111], v[128:131], v[144:147], v[108:111]
	v_mfma_f32_16x16x32_bf16 v[76:79], v[136:139], v[144:147], v[76:79]
	v_mfma_f32_16x16x32_bf16 v[104:107], v[128:131], v[152:155], v[104:107]
	v_mfma_f32_16x16x32_bf16 v[72:75], v[136:139], v[152:155], v[72:75]
	v_mfma_f32_16x16x32_bf16 v[100:103], v[128:131], v[160:163], v[100:103]
	v_mfma_f32_16x16x32_bf16 v[68:71], v[136:139], v[160:163], v[68:71]
	v_mfma_f32_16x16x32_bf16 v[96:99], v[128:131], v[178:181], v[96:99]
	v_mfma_f32_16x16x32_bf16 v[64:67], v[136:139], v[178:181], v[64:67]
	v_mfma_f32_16x16x32_bf16 v[108:111], v[132:135], v[148:151], v[108:111]
	v_mfma_f32_16x16x32_bf16 v[76:79], v[140:143], v[148:151], v[76:79]
	v_mfma_f32_16x16x32_bf16 v[104:107], v[132:135], v[156:159], v[104:107]
	v_mfma_f32_16x16x32_bf16 v[72:75], v[140:143], v[156:159], v[72:75]
	v_mfma_f32_16x16x32_bf16 v[100:103], v[132:135], v[174:177], v[100:103]
	v_mfma_f32_16x16x32_bf16 v[68:71], v[140:143], v[174:177], v[68:71]
	v_mfma_f32_16x16x32_bf16 v[96:99], v[132:135], v[182:185], v[96:99]
	v_mfma_f32_16x16x32_bf16 v[64:67], v[140:143], v[182:185], v[64:67]
	s_barrier
	s_add_u32 s6, s10, 0x160000
	s_addc_u32 s7, s11, 0
	s_mov_b32 m0, s77
	v_lshl_add_u64 v[128:129], s[6:7], 0, v[164:165]
	global_load_lds_dwordx4 v[128:129], off
	v_lshl_add_u64 v[128:129], s[6:7], 0, v[166:167]
	s_mov_b32 m0, s78
	s_nop 0
	global_load_lds_dwordx4 v[128:129], off
	s_waitcnt vmcnt(6)
	s_barrier
; #define WAIT_V(n) asm volatile("s_waitcnt vmcnt(" #n ")" ::: "memory")
; #define WAIT_L(n) asm volatile("s_waitcnt lgkmcnt(" #n ")" ::: "memory")
; #define BAR __builtin_amdgcn_s_barrier()
; #define SCHED __builtin_amdgcn_sched_barrier(0)
; template <class Get, class Epi>
; DI void gemm_stream(LAS unsigned char* lds, const int K, const int ld, Get get, Epi epi) {
;     ...
;             LDB(B0, 1, 0); SCHED; LDA(At, 1, 0); STAGE(SAo(0, 1), a2 + hstep);
;             WAIT_L(8); BAR; WAIT_L(0); MMA(0, 0, At, B0); BAR; SCHED;
;             LDB(B1, 1, 1); STAGE(SBo(1, 0), b3);
;             BAR; WAIT_L(0); MMA(0, 1, At, B1); BAR;
;             LDA(At, 1, 1); STAGE(SAo(1, 0), a3);
;             BAR; WAIT_L(0); MMA(1, 0, At, B0); BAR; SCHED;
;             STAGE(SBo(1, 1), b3 + hstep);
;             WAIT_V(6); BAR; MMA(1, 1, At, B1); BAR;
	v_mfma_f32_16x16x32_bf16 v[44:47], v[186:189], v[144:147], v[44:47]
	v_mfma_f32_16x16x32_bf16 v[12:15], v[194:197], v[144:147], v[12:15]
	v_mfma_f32_16x16x32_bf16 v[40:43], v[186:189], v[152:155], v[40:43]
	v_mfma_f32_16x16x32_bf16 v[8:11], v[194:197], v[152:155], v[8:11]
	v_mfma_f32_16x16x32_bf16 v[36:39], v[186:189], v[160:163], v[36:39]
	v_mfma_f32_16x16x32_bf16 v[4:7], v[194:197], v[160:163], v[4:7]
	v_mfma_f32_16x16x32_bf16 v[32:35], v[186:189], v[178:181], v[32:35]
	v_mfma_f32_16x16x32_bf16 v[0:3], v[194:197], v[178:181], v[0:3]
	v_mfma_f32_16x16x32_bf16 v[44:47], v[190:193], v[148:151], v[44:47]
	v_mfma_f32_16x16x32_bf16 v[12:15], v[202:205], v[148:151], v[12:15]
	v_mfma_f32_16x16x32_bf16 v[40:43], v[190:193], v[156:159], v[40:43]
	v_mfma_f32_16x16x32_bf16 v[8:11], v[202:205], v[156:159], v[8:11]
	v_mfma_f32_16x16x32_bf16 v[36:39], v[190:193], v[174:177], v[36:39]
	v_mfma_f32_16x16x32_bf16 v[4:7], v[202:205], v[174:177], v[4:7]
	v_mfma_f32_16x16x32_bf16 v[32:35], v[190:193], v[182:185], v[32:35]
	v_mfma_f32_16x16x32_bf16 v[0:3], v[202:205], v[182:185], v[0:3]
	s_add_i32 s17, 16, 0x18000
	v_add_u32_e32 v140, s17, v198
	s_barrier
	ds_read_b128 v[128:131], v140
	ds_read_b128 v[132:135], v140 offset:1024
	ds_read_b128 v[136:139], v140 offset:2048
	ds_read_b128 v[140:143], v140 offset:3072
	s_add_u32 s6, s12, 0x160000
	s_addc_u32 s7, s13, 0
	s_mov_b32 m0, s54
	v_lshl_add_u64 v[186:187], s[6:7], 0, v[164:165]
	ds_read_b128 v[144:147], v200 offset:32768
	ds_read_b128 v[148:151], v200 offset:33792
	ds_read_b128 v[152:155], v200 offset:34816
	ds_read_b128 v[156:159], v200 offset:35840
	ds_read_b128 v[160:163], v200 offset:36864
	ds_read_b128 v[174:177], v200 offset:37888
	ds_read_b128 v[178:181], v200 offset:38912
	ds_read_b128 v[182:185], v200 offset:39936
	global_load_lds_dwordx4 v[186:187], off
	v_lshl_add_u64 v[186:187], s[6:7], 0, v[166:167]
	s_mov_b32 m0, s55
	s_nop 0
	global_load_lds_dwordx4 v[186:187], off
	s_waitcnt lgkmcnt(8)
	s_barrier
	s_waitcnt lgkmcnt(0)
	v_mfma_f32_16x16x32_bf16 v[124:127], v[128:131], v[144:147], v[124:127]
	v_mfma_f32_16x16x32_bf16 v[92:95], v[136:139], v[144:147], v[92:95]
	v_mfma_f32_16x16x32_bf16 v[120:123], v[128:131], v[152:155], v[120:123]
	v_mfma_f32_16x16x32_bf16 v[88:91], v[136:139], v[152:155], v[88:91]
	v_mfma_f32_16x16x32_bf16 v[116:119], v[128:131], v[160:163], v[116:119]
	v_mfma_f32_16x16x32_bf16 v[84:87], v[136:139], v[160:163], v[84:87]
	v_mfma_f32_16x16x32_bf16 v[112:115], v[128:131], v[178:181], v[112:115]
	v_mfma_f32_16x16x32_bf16 v[80:83], v[136:139], v[178:181], v[80:83]
	v_mfma_f32_16x16x32_bf16 v[124:127], v[132:135], v[148:151], v[124:127]
	v_mfma_f32_16x16x32_bf16 v[92:95], v[140:143], v[148:151], v[92:95]
	v_mfma_f32_16x16x32_bf16 v[120:123], v[132:135], v[156:159], v[120:123]
	v_mfma_f32_16x16x32_bf16 v[88:91], v[140:143], v[156:159], v[88:91]
	v_mfma_f32_16x16x32_bf16 v[116:119], v[132:135], v[174:177], v[116:119]
	v_mfma_f32_16x16x32_bf16 v[84:87], v[140:143], v[174:177], v[84:87]
	v_mfma_f32_16x16x32_bf16 v[112:115], v[132:135], v[182:185], v[112:115]
	v_mfma_f32_16x16x32_bf16 v[80:83], v[140:143], v[182:185], v[80:83]
	s_barrier
	s_add_i32 s12, 16, 0x1c000
	s_add_i32 s6, s17, s21
	v_add_u32_e32 v202, s12, v198
	v_lshl_add_u64 v[208:209], v[208:209], 0, s[0:1]
	s_mov_b32 m0, s6
	ds_read_b128 v[186:189], v202
	ds_read_b128 v[190:193], v202 offset:1024
	ds_read_b128 v[194:197], v202 offset:2048
	ds_read_b128 v[202:205], v202 offset:3072
	global_load_lds_dwordx4 v[208:209], off
	v_lshl_add_u64 v[208:209], v[210:211], 0, s[0:1]
	s_add_i32 m0, s6, 0x2000
	s_nop 0
	global_load_lds_dwordx4 v[208:209], off
	s_barrier
	s_waitcnt lgkmcnt(0)
	v_mfma_f32_16x16x32_bf16 v[60:63], v[186:189], v[144:147], v[60:63]
	v_mfma_f32_16x16x32_bf16 v[28:31], v[194:197], v[144:147], v[28:31]
	v_mfma_f32_16x16x32_bf16 v[56:59], v[186:189], v[152:155], v[56:59]
	v_mfma_f32_16x16x32_bf16 v[24:27], v[194:197], v[152:155], v[24:27]
	v_mfma_f32_16x16x32_bf16 v[52:55], v[186:189], v[160:163], v[52:55]
	v_mfma_f32_16x16x32_bf16 v[20:23], v[194:197], v[160:163], v[20:23]
	v_mfma_f32_16x16x32_bf16 v[48:51], v[186:189], v[178:181], v[48:51]
	v_mfma_f32_16x16x32_bf16 v[16:19], v[194:197], v[178:181], v[16:19]
	v_mfma_f32_16x16x32_bf16 v[60:63], v[190:193], v[148:151], v[60:63]
	v_mfma_f32_16x16x32_bf16 v[28:31], v[202:205], v[148:151], v[28:31]
	v_mfma_f32_16x16x32_bf16 v[56:59], v[190:193], v[156:159], v[56:59]
	v_mfma_f32_16x16x32_bf16 v[24:27], v[202:205], v[156:159], v[24:27]
	v_mfma_f32_16x16x32_bf16 v[52:55], v[190:193], v[174:177], v[52:55]
	v_mfma_f32_16x16x32_bf16 v[20:23], v[202:205], v[174:177], v[20:23]
	v_mfma_f32_16x16x32_bf16 v[48:51], v[190:193], v[182:185], v[48:51]
	v_mfma_f32_16x16x32_bf16 v[16:19], v[202:205], v[182:185], v[16:19]
	s_mov_b32 m0, s56
	v_lshl_add_u64 v[208:209], v[212:213], 0, s[0:1]
	s_barrier
	ds_read_b128 v[144:147], v200 offset:49152
	ds_read_b128 v[148:151], v200 offset:50176
	ds_read_b128 v[152:155], v200 offset:51200
	ds_read_b128 v[156:159], v200 offset:52224
	ds_read_b128 v[160:163], v200 offset:53248
	ds_read_b128 v[174:177], v200 offset:54272
	ds_read_b128 v[178:181], v200 offset:55296
	ds_read_b128 v[182:185], v200 offset:56320
	global_load_lds_dwordx4 v[208:209], off
	v_lshl_add_u64 v[208:209], v[214:215], 0, s[0:1]
	s_mov_b32 m0, s57
	s_nop 0
	global_load_lds_dwordx4 v[208:209], off
	s_barrier
; #define WAIT_V(n) asm volatile("s_waitcnt vmcnt(" #n ")" ::: "memory")
; #define WAIT_L(n) asm volatile("s_waitcnt lgkmcnt(" #n ")" ::: "memory")
; #define BAR __builtin_amdgcn_s_barrier()
; #define SCHED __builtin_amdgcn_sched_barrier(0)
; #define EPI_DONE do { } while (0)
; template <class Get, class Epi>
; DI void gemm_stream(LAS unsigned char* lds, const int K, const int ld, Get get, Epi epi) {
;     ...
;             LDA(At, 1, 1); STAGE(SAo(1, 0), a3);
;             BAR; WAIT_L(0); MMA(1, 0, At, B0); BAR; SCHED;
;             STAGE(SBo(1, 1), b3 + hstep);
;             WAIT_V(6); BAR; MMA(1, 1, At, B1); BAR;
; DI void epi_resid(const Acc& acc, const P& p, int brow, int bcol, int layer, int gch, bool from_input) {
;     EPI_IDX
;     const float* gate = modv(p, layer, brow, gch);
; #pragma unroll
;     for (int bj = 0; bj < 2; ++bj)
; #pragma unroll
;         for (int n = 0; n < 2; ++n) {
;             const int c0 = bcol + bj * 128 + wc * 32 + n * 16 + fq * 4;
;             const f32x4 g = *(const f32x4*)(gate + c0);
;             f32x4 xv[2][4];
; #pragma unroll
;             for (int ai = 0; ai < 2; ++ai)
; #pragma unroll
;                 for (int m = 0; m < 4; ++m) {
;                     const int r = brow + ai * 128 + wr * 64 + m * 16 + fr;
;                     const float* sp = (from_input ? inrow(p, r) : xrow(p, r)) + c0;
;                     xv[ai][m] = *(const f32x4*)sp;
;                 }
;             __builtin_amdgcn_sched_barrier(0);
; #pragma unroll
;             for (int ai = 0; ai < 2; ++ai)
; #pragma unroll
;                 for (int m = 0; m < 4; ++m) {
;                     const int r = brow + ai * 128 + wr * 64 + m * 16 + fr;
;                     *(f32x4*)(xrow(p, r) + c0) = xv[ai][m] + g * acc[ai][bj][m][n];
;                 }
;             __builtin_amdgcn_sched_barrier(0);
;         }
;     EPI_DONE;
; }
	s_waitcnt lgkmcnt(0)
	v_mfma_f32_16x16x32_bf16 v[108:111], v[128:131], v[144:147], v[108:111]
	v_mfma_f32_16x16x32_bf16 v[76:79], v[136:139], v[144:147], v[76:79]
	v_mfma_f32_16x16x32_bf16 v[104:107], v[128:131], v[152:155], v[104:107]
	v_mfma_f32_16x16x32_bf16 v[72:75], v[136:139], v[152:155], v[72:75]
	v_mfma_f32_16x16x32_bf16 v[100:103], v[128:131], v[160:163], v[100:103]
	v_mfma_f32_16x16x32_bf16 v[68:71], v[136:139], v[160:163], v[68:71]
	v_mfma_f32_16x16x32_bf16 v[96:99], v[128:131], v[178:181], v[96:99]
	v_mfma_f32_16x16x32_bf16 v[64:67], v[136:139], v[178:181], v[64:67]
	v_mfma_f32_16x16x32_bf16 v[108:111], v[132:135], v[148:151], v[108:111]
	v_mfma_f32_16x16x32_bf16 v[76:79], v[140:143], v[148:151], v[76:79]
	v_mfma_f32_16x16x32_bf16 v[104:107], v[132:135], v[156:159], v[104:107]
	v_mfma_f32_16x16x32_bf16 v[72:75], v[140:143], v[156:159], v[72:75]
	v_mfma_f32_16x16x32_bf16 v[100:103], v[132:135], v[174:177], v[100:103]
	v_mfma_f32_16x16x32_bf16 v[68:71], v[140:143], v[174:177], v[68:71]
	v_mfma_f32_16x16x32_bf16 v[96:99], v[132:135], v[182:185], v[96:99]
	v_mfma_f32_16x16x32_bf16 v[64:67], v[140:143], v[182:185], v[64:67]
	s_barrier
	s_add_u32 s6, s10, 0x160080
	s_addc_u32 s7, s11, 0
	s_add_i32 s10, s12, s21
	v_lshl_add_u64 v[128:129], s[6:7], 0, v[164:165]
	s_mov_b32 m0, s10
	s_nop 0
	global_load_lds_dwordx4 v[128:129], off
	v_lshl_add_u64 v[128:129], s[6:7], 0, v[166:167]
	s_add_i32 m0, s10, 0x2000
	s_nop 0
	global_load_lds_dwordx4 v[128:129], off
	s_waitcnt vmcnt(6)
	s_barrier
	v_mfma_f32_16x16x32_bf16 v[44:47], v[186:189], v[144:147], v[44:47]
	v_mfma_f32_16x16x32_bf16 v[12:15], v[194:197], v[144:147], v[12:15]
	v_mfma_f32_16x16x32_bf16 v[40:43], v[186:189], v[152:155], v[40:43]
	v_mfma_f32_16x16x32_bf16 v[8:11], v[194:197], v[152:155], v[8:11]
	v_mfma_f32_16x16x32_bf16 v[36:39], v[186:189], v[160:163], v[36:39]
	v_mfma_f32_16x16x32_bf16 v[4:7], v[194:197], v[160:163], v[4:7]
	v_mfma_f32_16x16x32_bf16 v[32:35], v[186:189], v[178:181], v[32:35]
	v_mfma_f32_16x16x32_bf16 v[0:3], v[194:197], v[178:181], v[0:3]
	v_mfma_f32_16x16x32_bf16 v[44:47], v[190:193], v[148:151], v[44:47]
	v_mfma_f32_16x16x32_bf16 v[12:15], v[202:205], v[148:151], v[12:15]
	v_mfma_f32_16x16x32_bf16 v[40:43], v[190:193], v[156:159], v[40:43]
	v_mfma_f32_16x16x32_bf16 v[8:11], v[202:205], v[156:159], v[8:11]
	v_mfma_f32_16x16x32_bf16 v[36:39], v[190:193], v[174:177], v[36:39]
	v_mfma_f32_16x16x32_bf16 v[4:7], v[202:205], v[174:177], v[4:7]
	v_mfma_f32_16x16x32_bf16 v[32:35], v[190:193], v[182:185], v[32:35]
	v_mfma_f32_16x16x32_bf16 v[0:3], v[202:205], v[182:185], v[0:3]
	s_add_i32 s16, s16, 2
	s_add_u32 s14, s14, 0x100
	s_addc_u32 s15, s15, 0
	s_cmpk_gt_u32 s16, 0x55
	s_mov_b64 s[6:7], s[8:9]
	s_barrier
	s_cbranch_scc0 .LBB0_1697
	s_lshl_b32 s12, s3, 21
	s_lshl_b32 s13, s2, 10
	s_lshr_b32 s16, s3, 4
	s_add_u32 s12, s12, s13
	s_mul_i32 s16, s16, 6
	s_add_i32 s16, s16, 5
	s_lshl_b32 s16, s16, 13
	s_add_u32 s16, s16, s13
	s_add_u32 s10, s26, s16
	s_addc_u32 s11, s27, 0
	s_add_u32 s6, s24, s12
	s_addc_u32 s7, s25, 0
	v_lshrrev_b32_e32 v224, 6, v206
	v_and_b32_e32 v225, 3, v224
	v_lshrrev_b32_e32 v224, 2, v224
	v_and_b32_e32 v205, 15, v206
	v_bfe_u32 v226, v206, 4, 2
	v_lshl_add_u32 v225, v225, 3, v226
	v_lshl_add_u32 v224, v224, 6, v205
	v_lshlrev_b32_e32 v205, 4, v225
	v_lshl_add_u32 v203, v224, 13, v205
	v_mov_b32_e32 v204, v203
	global_load_dwordx4 v[128:131], v205, s[10:11] offset:0
	global_load_dwordx4 v[132:135], v205, s[10:11] offset:64
	global_load_dwordx4 v[136:139], v205, s[10:11] offset:512
	global_load_dwordx4 v[140:143], v205, s[10:11] offset:576
	global_load_dwordx4 v[144:147], v203, s[6:7] offset:0
	global_load_dwordx4 v[148:151], v203, s[6:7] offset:64
	global_load_dwordx4 v[152:155], v203, s[6:7] offset:512
	global_load_dwordx4 v[156:159], v203, s[6:7] offset:576
	v_add_u32_e32 v203, 0x20000, v203
	global_load_dwordx4 v[160:163], v203, s[6:7] offset:0
	global_load_dwordx4 v[174:177], v203, s[6:7] offset:64
	global_load_dwordx4 v[178:181], v203, s[6:7] offset:512
	global_load_dwordx4 v[182:185], v203, s[6:7] offset:576
	v_add_u32_e32 v203, 0x20000, v203
	global_load_dwordx4 v[186:189], v203, s[6:7] offset:0
	global_load_dwordx4 v[190:193], v203, s[6:7] offset:64
	global_load_dwordx4 v[194:197], v203, s[6:7] offset:512
	global_load_dwordx4 v[208:211], v203, s[6:7] offset:576
	v_add_u32_e32 v203, 0x20000, v203
	global_load_dwordx4 v[212:215], v203, s[6:7] offset:0
	global_load_dwordx4 v[216:219], v203, s[6:7] offset:64
	global_load_dwordx4 v[220:223], v203, s[6:7] offset:512
	global_load_dwordx4 v[224:227], v203, s[6:7] offset:576
	v_add_u32_e32 v203, 0xa0000, v203
	s_waitcnt vmcnt(12)
	v_pk_fma_f32 v[124:125], v[124:125], v[128:129], v[144:145]
	v_pk_fma_f32 v[126:127], v[126:127], v[130:131], v[146:147]
	v_pk_fma_f32 v[92:93], v[92:93], v[132:133], v[148:149]
	v_pk_fma_f32 v[94:95], v[94:95], v[134:135], v[150:151]
	v_pk_fma_f32 v[60:61], v[60:61], v[136:137], v[152:153]
	v_pk_fma_f32 v[62:63], v[62:63], v[138:139], v[154:155]
	v_pk_fma_f32 v[28:29], v[28:29], v[140:141], v[156:157]
	v_pk_fma_f32 v[30:31], v[30:31], v[142:143], v[158:159]
	global_store_dwordx4 v204, v[124:127], s[6:7] offset:0
	global_store_dwordx4 v204, v[92:95], s[6:7] offset:64
	global_store_dwordx4 v204, v[60:63], s[6:7] offset:512
	global_store_dwordx4 v204, v[28:31], s[6:7] offset:576
	v_add_u32_e32 v204, 0x20000, v204
	global_load_dwordx4 v[144:147], v203, s[6:7] offset:0
	global_load_dwordx4 v[148:151], v203, s[6:7] offset:64
	global_load_dwordx4 v[152:155], v203, s[6:7] offset:512
	global_load_dwordx4 v[156:159], v203, s[6:7] offset:576
	v_add_u32_e32 v203, 0x20000, v203
	s_waitcnt vmcnt(16)
; DI void epi_resid(const Acc& acc, const P& p, int brow, int bcol, int layer, int gch, bool from_input) {
;     ...
;             for (int ai = 0; ai < 2; ++ai)
; #pragma unroll
;                 for (int m = 0; m < 4; ++m) {
;                     const int r = brow + ai * 128 + wr * 64 + m * 16 + fr;
;                     *(f32x4*)(xrow(p, r) + c0) = xv[ai][m] + g * acc[ai][bj][m][n];
;                 }
	v_pk_fma_f32 v[120:121], v[120:121], v[128:129], v[160:161]
	v_pk_fma_f32 v[122:123], v[122:123], v[130:131], v[162:163]
	v_pk_fma_f32 v[88:89], v[88:89], v[132:133], v[174:175]
	v_pk_fma_f32 v[90:91], v[90:91], v[134:135], v[176:177]
	v_pk_fma_f32 v[56:57], v[56:57], v[136:137], v[178:179]
	v_pk_fma_f32 v[58:59], v[58:59], v[138:139], v[180:181]
	v_pk_fma_f32 v[24:25], v[24:25], v[140:141], v[182:183]
	v_pk_fma_f32 v[26:27], v[26:27], v[142:143], v[184:185]
	global_store_dwordx4 v204, v[120:123], s[6:7] offset:0
	global_store_dwordx4 v204, v[88:91], s[6:7] offset:64
	global_store_dwordx4 v204, v[56:59], s[6:7] offset:512
	global_store_dwordx4 v204, v[24:27], s[6:7] offset:576
	v_add_u32_e32 v204, 0x20000, v204
	global_load_dwordx4 v[160:163], v203, s[6:7] offset:0
	global_load_dwordx4 v[174:177], v203, s[6:7] offset:64
	global_load_dwordx4 v[178:181], v203, s[6:7] offset:512
	global_load_dwordx4 v[182:185], v203, s[6:7] offset:576
	v_add_u32_e32 v203, 0x20000, v203
	s_waitcnt vmcnt(20)
	v_pk_fma_f32 v[116:117], v[116:117], v[128:129], v[186:187]
	v_pk_fma_f32 v[118:119], v[118:119], v[130:131], v[188:189]
	v_pk_fma_f32 v[84:85], v[84:85], v[132:133], v[190:191]
	v_pk_fma_f32 v[86:87], v[86:87], v[134:135], v[192:193]
	v_pk_fma_f32 v[52:53], v[52:53], v[136:137], v[194:195]
	v_pk_fma_f32 v[54:55], v[54:55], v[138:139], v[196:197]
	v_pk_fma_f32 v[20:21], v[20:21], v[140:141], v[208:209]
	v_pk_fma_f32 v[22:23], v[22:23], v[142:143], v[210:211]
	global_store_dwordx4 v204, v[116:119], s[6:7] offset:0
	global_store_dwordx4 v204, v[84:87], s[6:7] offset:64
	global_store_dwordx4 v204, v[52:55], s[6:7] offset:512
	global_store_dwordx4 v204, v[20:23], s[6:7] offset:576
	v_add_u32_e32 v204, 0x20000, v204
	global_load_dwordx4 v[186:189], v203, s[6:7] offset:0
	global_load_dwordx4 v[190:193], v203, s[6:7] offset:64
	global_load_dwordx4 v[194:197], v203, s[6:7] offset:512
	global_load_dwordx4 v[208:211], v203, s[6:7] offset:576
	v_add_u32_e32 v203, 0x20000, v203
	s_waitcnt vmcnt(24)
	v_pk_fma_f32 v[112:113], v[112:113], v[128:129], v[212:213]
	v_pk_fma_f32 v[114:115], v[114:115], v[130:131], v[214:215]
	v_pk_fma_f32 v[80:81], v[80:81], v[132:133], v[216:217]
	v_pk_fma_f32 v[82:83], v[82:83], v[134:135], v[218:219]
	v_pk_fma_f32 v[48:49], v[48:49], v[136:137], v[220:221]
	v_pk_fma_f32 v[50:51], v[50:51], v[138:139], v[222:223]
	v_pk_fma_f32 v[16:17], v[16:17], v[140:141], v[224:225]
	v_pk_fma_f32 v[18:19], v[18:19], v[142:143], v[226:227]
	global_store_dwordx4 v204, v[112:115], s[6:7] offset:0
	global_store_dwordx4 v204, v[80:83], s[6:7] offset:64
	global_store_dwordx4 v204, v[48:51], s[6:7] offset:512
	global_store_dwordx4 v204, v[16:19], s[6:7] offset:576
	v_add_u32_e32 v204, 0xa0000, v204
	global_load_dwordx4 v[212:215], v203, s[6:7] offset:0
	global_load_dwordx4 v[216:219], v203, s[6:7] offset:64
	global_load_dwordx4 v[220:223], v203, s[6:7] offset:512
	global_load_dwordx4 v[224:227], v203, s[6:7] offset:576
	s_waitcnt vmcnt(24)
	v_pk_fma_f32 v[108:109], v[108:109], v[128:129], v[144:145]
	v_pk_fma_f32 v[110:111], v[110:111], v[130:131], v[146:147]
	v_pk_fma_f32 v[76:77], v[76:77], v[132:133], v[148:149]
	v_pk_fma_f32 v[78:79], v[78:79], v[134:135], v[150:151]
	v_pk_fma_f32 v[44:45], v[44:45], v[136:137], v[152:153]
	v_pk_fma_f32 v[46:47], v[46:47], v[138:139], v[154:155]
	v_pk_fma_f32 v[12:13], v[12:13], v[140:141], v[156:157]
	v_pk_fma_f32 v[14:15], v[14:15], v[142:143], v[158:159]
	global_store_dwordx4 v204, v[108:111], s[6:7] offset:0
	global_store_dwordx4 v204, v[76:79], s[6:7] offset:64
	global_store_dwordx4 v204, v[44:47], s[6:7] offset:512
	global_store_dwordx4 v204, v[12:15], s[6:7] offset:576
	v_add_u32_e32 v204, 0x20000, v204
	s_waitcnt vmcnt(20)
	v_pk_fma_f32 v[104:105], v[104:105], v[128:129], v[160:161]
	v_pk_fma_f32 v[106:107], v[106:107], v[130:131], v[162:163]
	v_pk_fma_f32 v[72:73], v[72:73], v[132:133], v[174:175]
	v_pk_fma_f32 v[74:75], v[74:75], v[134:135], v[176:177]
	v_pk_fma_f32 v[40:41], v[40:41], v[136:137], v[178:179]
	v_pk_fma_f32 v[42:43], v[42:43], v[138:139], v[180:181]
	v_pk_fma_f32 v[8:9], v[8:9], v[140:141], v[182:183]
	v_pk_fma_f32 v[10:11], v[10:11], v[142:143], v[184:185]
	global_store_dwordx4 v204, v[104:107], s[6:7] offset:0
	global_store_dwordx4 v204, v[72:75], s[6:7] offset:64
	global_store_dwordx4 v204, v[40:43], s[6:7] offset:512
	global_store_dwordx4 v204, v[8:11], s[6:7] offset:576
	v_add_u32_e32 v204, 0x20000, v204
	s_waitcnt vmcnt(16)
	v_pk_fma_f32 v[100:101], v[100:101], v[128:129], v[186:187]
	v_pk_fma_f32 v[102:103], v[102:103], v[130:131], v[188:189]
	v_pk_fma_f32 v[68:69], v[68:69], v[132:133], v[190:191]
	v_pk_fma_f32 v[70:71], v[70:71], v[134:135], v[192:193]
	v_pk_fma_f32 v[36:37], v[36:37], v[136:137], v[194:195]
	v_pk_fma_f32 v[38:39], v[38:39], v[138:139], v[196:197]
	v_pk_fma_f32 v[4:5], v[4:5], v[140:141], v[208:209]
	v_pk_fma_f32 v[6:7], v[6:7], v[142:143], v[210:211]
	global_store_dwordx4 v204, v[100:103], s[6:7] offset:0
	global_store_dwordx4 v204, v[68:71], s[6:7] offset:64
	global_store_dwordx4 v204, v[36:39], s[6:7] offset:512
	global_store_dwordx4 v204, v[4:7], s[6:7] offset:576
	v_add_u32_e32 v204, 0x20000, v204
	s_waitcnt vmcnt(12)
	v_pk_fma_f32 v[96:97], v[96:97], v[128:129], v[212:213]
	v_pk_fma_f32 v[98:99], v[98:99], v[130:131], v[214:215]
	v_pk_fma_f32 v[64:65], v[64:65], v[132:133], v[216:217]
	v_pk_fma_f32 v[66:67], v[66:67], v[134:135], v[218:219]
	v_pk_fma_f32 v[32:33], v[32:33], v[136:137], v[220:221]
	v_pk_fma_f32 v[34:35], v[34:35], v[138:139], v[222:223]
	v_pk_fma_f32 v[0:1], v[0:1], v[140:141], v[224:225]
	v_pk_fma_f32 v[2:3], v[2:3], v[142:143], v[226:227]
	global_store_dwordx4 v204, v[96:99], s[6:7] offset:0
	global_store_dwordx4 v204, v[64:67], s[6:7] offset:64
	global_store_dwordx4 v204, v[32:35], s[6:7] offset:512
	global_store_dwordx4 v204, v[0:3], s[6:7] offset:576
	s_branch .Lresid_latch_ffndL0

; template <class Get, class Epi>
; DI void gemm_stream(LAS unsigned char* lds, const int K, const int ld, Get get, Epi epi) {
;     ...
;         epi(acc, cur);
;         if (!has_next) break;
;         ZERO_ACC;
;         cur = nxt; cA = nA; cB = nB; ++ui;
.LBB0_2666:
.Lresid_latch_wout1:
	s_and_b64 vcc, exec, s[4:5]
	s_mov_b32 s2, s70
	s_mov_b32 s3, s71
	s_mov_b64 s[8:9], s[40:41]
	s_mov_b64 s[6:7], s[38:39]
	s_cbranch_vccnz .LBB0_2927

; #define WAIT_V(n) asm volatile("s_waitcnt vmcnt(" #n ")" ::: "memory")
; #define WAIT_L(n) asm volatile("s_waitcnt lgkmcnt(" #n ")" ::: "memory")
; #define BAR __builtin_amdgcn_s_barrier()
; #define SCHED __builtin_amdgcn_sched_barrier(0)
; template <class Get, class Epi>
; DI void gemm_stream(LAS unsigned char* lds, const int K, const int ld, Get get, Epi epi) {
;     ...
;             LDB(B0, 0, 0); SCHED; LDA(At, 0, 0); STAGE(SAo(1, 1), a1 + hstep);
;             WAIT_L(8); BAR; WAIT_L(0); MMA(0, 0, At, B0); BAR; SCHED;
;             LDB(B1, 0, 1); STAGE(SBo(0, 0), b2);
;             BAR; WAIT_L(0); MMA(0, 1, At, B1); BAR;
;             LDA(At, 0, 1); STAGE(SAo(0, 0), a2);
;             BAR; WAIT_L(0); MMA(1, 0, At, B0); BAR; SCHED;
;             STAGE(SBo(0, 1), b2 + hstep);
;             WAIT_V(6); BAR; MMA(1, 1, At, B1); BAR;
;             LDB(B0, 1, 0); SCHED; LDA(At, 1, 0); STAGE(SAo(0, 1), a2 + hstep);
;             WAIT_L(8); BAR; WAIT_L(0); MMA(0, 0, At, B0); BAR; SCHED;
;             LDB(B1, 1, 1); STAGE(SBo(1, 0), b3);
;             BAR; WAIT_L(0); MMA(0, 1, At, B1); BAR;
.LBB0_2670:
	ds_read_b128 v[128:131], v198
	ds_read_b128 v[132:135], v198 offset:1024
	ds_read_b128 v[136:139], v198 offset:2048
	ds_read_b128 v[140:143], v198 offset:3072
	s_add_u32 s8, s6, 0x100
	s_addc_u32 s9, s7, 0
	s_cmp_eq_u32 s16, 60
	s_cselect_b32 s13, s39, s9
	s_cselect_b32 s12, s38, s8
	s_cselect_b32 s11, s41, s15
	s_cselect_b32 s10, s40, s14
	s_mov_b32 m0, s52
	v_lshl_add_u64 v[186:187], s[6:7], 0, v[168:169]
	ds_read_b128 v[144:147], v199
	ds_read_b128 v[148:151], v199 offset:1024
	ds_read_b128 v[152:155], v199 offset:2048
	ds_read_b128 v[156:159], v199 offset:3072
	ds_read_b128 v[160:163], v199 offset:4096
	ds_read_b128 v[174:177], v199 offset:5120
	ds_read_b128 v[178:181], v199 offset:6144
	ds_read_b128 v[182:185], v199 offset:7168
	global_load_lds_dwordx4 v[186:187], off
	v_lshl_add_u64 v[186:187], s[6:7], 0, v[170:171]
	s_mov_b32 m0, s53
	s_nop 0
	global_load_lds_dwordx4 v[186:187], off
	s_waitcnt lgkmcnt(8)
	s_barrier
	s_waitcnt lgkmcnt(0)
	v_mfma_f32_16x16x32_bf16 v[124:127], v[128:131], v[144:147], v[124:127]
	v_mfma_f32_16x16x32_bf16 v[92:95], v[136:139], v[144:147], v[92:95]
	v_mfma_f32_16x16x32_bf16 v[120:123], v[128:131], v[152:155], v[120:123]
	v_mfma_f32_16x16x32_bf16 v[88:91], v[136:139], v[152:155], v[88:91]
	v_mfma_f32_16x16x32_bf16 v[116:119], v[128:131], v[160:163], v[116:119]
	v_mfma_f32_16x16x32_bf16 v[84:87], v[136:139], v[160:163], v[84:87]
	v_mfma_f32_16x16x32_bf16 v[112:115], v[128:131], v[178:181], v[112:115]
	v_mfma_f32_16x16x32_bf16 v[80:83], v[136:139], v[178:181], v[80:83]
	v_mfma_f32_16x16x32_bf16 v[124:127], v[132:135], v[148:151], v[124:127]
	v_mfma_f32_16x16x32_bf16 v[92:95], v[140:143], v[148:151], v[92:95]
	v_mfma_f32_16x16x32_bf16 v[120:123], v[132:135], v[156:159], v[120:123]
	v_mfma_f32_16x16x32_bf16 v[88:91], v[140:143], v[156:159], v[88:91]
	v_mfma_f32_16x16x32_bf16 v[116:119], v[132:135], v[174:177], v[116:119]
	v_mfma_f32_16x16x32_bf16 v[84:87], v[140:143], v[174:177], v[84:87]
	v_mfma_f32_16x16x32_bf16 v[112:115], v[132:135], v[182:185], v[112:115]
	v_mfma_f32_16x16x32_bf16 v[80:83], v[140:143], v[182:185], v[80:83]
	s_barrier
	s_mov_b32 m0, s58
	v_lshl_add_u64 v[204:205], s[10:11], 0, v[164:165]
	ds_read_b128 v[186:189], v200
	ds_read_b128 v[190:193], v200 offset:1024
	ds_read_b128 v[194:197], v200 offset:2048
	ds_read_b128 v[208:211], v200 offset:3072
	global_load_lds_dwordx4 v[204:205], off
	v_lshl_add_u64 v[212:213], s[10:11], 0, v[166:167]
	s_mov_b32 m0, s59
	s_nop 0
	global_load_lds_dwordx4 v[212:213], off
	s_barrier
	s_waitcnt lgkmcnt(0)
	v_mfma_f32_16x16x32_bf16 v[60:63], v[186:189], v[144:147], v[60:63]
	v_mfma_f32_16x16x32_bf16 v[28:31], v[194:197], v[144:147], v[28:31]
	v_mfma_f32_16x16x32_bf16 v[56:59], v[186:189], v[152:155], v[56:59]
	v_mfma_f32_16x16x32_bf16 v[24:27], v[194:197], v[152:155], v[24:27]
	v_mfma_f32_16x16x32_bf16 v[52:55], v[186:189], v[160:163], v[52:55]
	v_mfma_f32_16x16x32_bf16 v[20:23], v[194:197], v[160:163], v[20:23]
	v_mfma_f32_16x16x32_bf16 v[48:51], v[186:189], v[178:181], v[48:51]
	v_mfma_f32_16x16x32_bf16 v[16:19], v[194:197], v[178:181], v[16:19]
	v_mfma_f32_16x16x32_bf16 v[60:63], v[190:193], v[148:151], v[60:63]
	v_mfma_f32_16x16x32_bf16 v[28:31], v[208:211], v[148:151], v[28:31]
	v_mfma_f32_16x16x32_bf16 v[56:59], v[190:193], v[156:159], v[56:59]
	v_mfma_f32_16x16x32_bf16 v[24:27], v[208:211], v[156:159], v[24:27]
	v_mfma_f32_16x16x32_bf16 v[52:55], v[190:193], v[174:177], v[52:55]
	v_mfma_f32_16x16x32_bf16 v[20:23], v[208:211], v[174:177], v[20:23]
	v_mfma_f32_16x16x32_bf16 v[48:51], v[190:193], v[182:185], v[48:51]
	v_mfma_f32_16x16x32_bf16 v[16:19], v[208:211], v[182:185], v[16:19]
	s_mov_b32 m0, s35
	v_lshl_add_u64 v[214:215], s[12:13], 0, v[164:165]
	s_barrier
	ds_read_b128 v[144:147], v199 offset:16384
	ds_read_b128 v[148:151], v199 offset:17408
	ds_read_b128 v[152:155], v199 offset:18432
	ds_read_b128 v[156:159], v199 offset:19456
	ds_read_b128 v[160:163], v199 offset:20480
	ds_read_b128 v[174:177], v199 offset:21504
	ds_read_b128 v[178:181], v199 offset:22528
	ds_read_b128 v[182:185], v199 offset:23552
	global_load_lds_dwordx4 v[214:215], off
	v_lshl_add_u64 v[216:217], s[12:13], 0, v[166:167]
	s_mov_b32 m0, s44
	s_nop 0
	global_load_lds_dwordx4 v[216:217], off
	s_barrier
	s_waitcnt lgkmcnt(0)
	v_mfma_f32_16x16x32_bf16 v[108:111], v[128:131], v[144:147], v[108:111]
	v_mfma_f32_16x16x32_bf16 v[76:79], v[136:139], v[144:147], v[76:79]
	v_mfma_f32_16x16x32_bf16 v[104:107], v[128:131], v[152:155], v[104:107]
	v_mfma_f32_16x16x32_bf16 v[72:75], v[136:139], v[152:155], v[72:75]
	v_mfma_f32_16x16x32_bf16 v[100:103], v[128:131], v[160:163], v[100:103]
	v_mfma_f32_16x16x32_bf16 v[68:71], v[136:139], v[160:163], v[68:71]
	v_mfma_f32_16x16x32_bf16 v[96:99], v[128:131], v[178:181], v[96:99]
	v_mfma_f32_16x16x32_bf16 v[64:67], v[136:139], v[178:181], v[64:67]
	v_mfma_f32_16x16x32_bf16 v[108:111], v[132:135], v[148:151], v[108:111]
	v_mfma_f32_16x16x32_bf16 v[76:79], v[140:143], v[148:151], v[76:79]
	v_mfma_f32_16x16x32_bf16 v[104:107], v[132:135], v[156:159], v[104:107]
	v_mfma_f32_16x16x32_bf16 v[72:75], v[140:143], v[156:159], v[72:75]
	v_mfma_f32_16x16x32_bf16 v[100:103], v[132:135], v[174:177], v[100:103]
	v_mfma_f32_16x16x32_bf16 v[68:71], v[140:143], v[174:177], v[68:71]
	v_mfma_f32_16x16x32_bf16 v[96:99], v[132:135], v[182:185], v[96:99]
	v_mfma_f32_16x16x32_bf16 v[64:67], v[140:143], v[182:185], v[64:67]
	s_barrier
	s_add_u32 s6, s10, 0x100000
	s_addc_u32 s7, s11, 0
	s_mov_b32 m0, s60
	v_lshl_add_u64 v[128:129], s[6:7], 0, v[164:165]
	global_load_lds_dwordx4 v[128:129], off
	v_lshl_add_u64 v[128:129], s[6:7], 0, v[166:167]
	s_mov_b32 m0, s61
	s_nop 0
	global_load_lds_dwordx4 v[128:129], off
	s_waitcnt vmcnt(6)
	s_barrier
; #define WAIT_V(n) asm volatile("s_waitcnt vmcnt(" #n ")" ::: "memory")
; #define WAIT_L(n) asm volatile("s_waitcnt lgkmcnt(" #n ")" ::: "memory")
; #define BAR __builtin_amdgcn_s_barrier()
; #define SCHED __builtin_amdgcn_sched_barrier(0)
; template <class Get, class Epi>
; DI void gemm_stream(LAS unsigned char* lds, const int K, const int ld, Get get, Epi epi) {
;     ...
;             LDB(B0, 1, 0); SCHED; LDA(At, 1, 0); STAGE(SAo(0, 1), a2 + hstep);
;             WAIT_L(8); BAR; WAIT_L(0); MMA(0, 0, At, B0); BAR; SCHED;
;             LDB(B1, 1, 1); STAGE(SBo(1, 0), b3);
;             BAR; WAIT_L(0); MMA(0, 1, At, B1); BAR;
;             LDA(At, 1, 1); STAGE(SAo(1, 0), a3);
;             BAR; WAIT_L(0); MMA(1, 0, At, B0); BAR; SCHED;
;             STAGE(SBo(1, 1), b3 + hstep);
;             WAIT_V(6); BAR; MMA(1, 1, At, B1); BAR;
	v_mfma_f32_16x16x32_bf16 v[44:47], v[186:189], v[144:147], v[44:47]
	v_mfma_f32_16x16x32_bf16 v[12:15], v[194:197], v[144:147], v[12:15]
	v_mfma_f32_16x16x32_bf16 v[40:43], v[186:189], v[152:155], v[40:43]
	v_mfma_f32_16x16x32_bf16 v[8:11], v[194:197], v[152:155], v[8:11]
	v_mfma_f32_16x16x32_bf16 v[36:39], v[186:189], v[160:163], v[36:39]
	v_mfma_f32_16x16x32_bf16 v[4:7], v[194:197], v[160:163], v[4:7]
	v_mfma_f32_16x16x32_bf16 v[32:35], v[186:189], v[178:181], v[32:35]
	v_mfma_f32_16x16x32_bf16 v[0:3], v[194:197], v[178:181], v[0:3]
	v_mfma_f32_16x16x32_bf16 v[44:47], v[190:193], v[148:151], v[44:47]
	v_mfma_f32_16x16x32_bf16 v[12:15], v[208:211], v[148:151], v[12:15]
	v_mfma_f32_16x16x32_bf16 v[40:43], v[190:193], v[156:159], v[40:43]
	v_mfma_f32_16x16x32_bf16 v[8:11], v[208:211], v[156:159], v[8:11]
	v_mfma_f32_16x16x32_bf16 v[36:39], v[190:193], v[174:177], v[36:39]
	v_mfma_f32_16x16x32_bf16 v[4:7], v[208:211], v[174:177], v[4:7]
	v_mfma_f32_16x16x32_bf16 v[32:35], v[190:193], v[182:185], v[32:35]
	v_mfma_f32_16x16x32_bf16 v[0:3], v[208:211], v[182:185], v[0:3]
	s_barrier
	ds_read_b128 v[128:131], v201
	ds_read_b128 v[132:135], v201 offset:1024
	ds_read_b128 v[136:139], v201 offset:2048
	ds_read_b128 v[140:143], v201 offset:3072
	s_add_u32 s6, s12, 0x100000
	s_addc_u32 s7, s13, 0
	s_mov_b32 m0, s45
	v_lshl_add_u64 v[186:187], s[6:7], 0, v[164:165]
	ds_read_b128 v[144:147], v199 offset:32768
	ds_read_b128 v[148:151], v199 offset:33792
	ds_read_b128 v[152:155], v199 offset:34816
	ds_read_b128 v[156:159], v199 offset:35840
	ds_read_b128 v[160:163], v199 offset:36864
	ds_read_b128 v[174:177], v199 offset:37888
	ds_read_b128 v[178:181], v199 offset:38912
	ds_read_b128 v[182:185], v199 offset:39936
	global_load_lds_dwordx4 v[186:187], off
	v_lshl_add_u64 v[186:187], s[6:7], 0, v[166:167]
	s_mov_b32 m0, s46
	s_nop 0
	global_load_lds_dwordx4 v[186:187], off
	s_waitcnt lgkmcnt(8)
	s_barrier
	s_waitcnt lgkmcnt(0)
	v_mfma_f32_16x16x32_bf16 v[124:127], v[128:131], v[144:147], v[124:127]
	v_mfma_f32_16x16x32_bf16 v[92:95], v[136:139], v[144:147], v[92:95]
	v_mfma_f32_16x16x32_bf16 v[120:123], v[128:131], v[152:155], v[120:123]
	v_mfma_f32_16x16x32_bf16 v[88:91], v[136:139], v[152:155], v[88:91]
	v_mfma_f32_16x16x32_bf16 v[116:119], v[128:131], v[160:163], v[116:119]
	v_mfma_f32_16x16x32_bf16 v[84:87], v[136:139], v[160:163], v[84:87]
	v_mfma_f32_16x16x32_bf16 v[112:115], v[128:131], v[178:181], v[112:115]
	v_mfma_f32_16x16x32_bf16 v[80:83], v[136:139], v[178:181], v[80:83]
	v_mfma_f32_16x16x32_bf16 v[124:127], v[132:135], v[148:151], v[124:127]
	v_mfma_f32_16x16x32_bf16 v[92:95], v[140:143], v[148:151], v[92:95]
	v_mfma_f32_16x16x32_bf16 v[120:123], v[132:135], v[156:159], v[120:123]
	v_mfma_f32_16x16x32_bf16 v[88:91], v[140:143], v[156:159], v[88:91]
	v_mfma_f32_16x16x32_bf16 v[116:119], v[132:135], v[174:177], v[116:119]
	v_mfma_f32_16x16x32_bf16 v[84:87], v[140:143], v[174:177], v[84:87]
	v_mfma_f32_16x16x32_bf16 v[112:115], v[132:135], v[182:185], v[112:115]
	v_mfma_f32_16x16x32_bf16 v[80:83], v[140:143], v[182:185], v[80:83]
	s_barrier
	s_mov_b32 m0, s64
	v_lshl_add_u64 v[204:205], v[204:205], 0, s[0:1]
	ds_read_b128 v[186:189], v202
	ds_read_b128 v[190:193], v202 offset:1024
	ds_read_b128 v[194:197], v202 offset:2048
	ds_read_b128 v[208:211], v202 offset:3072
	global_load_lds_dwordx4 v[204:205], off
	v_lshl_add_u64 v[204:205], v[212:213], 0, s[0:1]
	s_mov_b32 m0, s65
	s_nop 0
	global_load_lds_dwordx4 v[204:205], off
	s_barrier
	s_waitcnt lgkmcnt(0)
	v_mfma_f32_16x16x32_bf16 v[60:63], v[186:189], v[144:147], v[60:63]
	v_mfma_f32_16x16x32_bf16 v[28:31], v[194:197], v[144:147], v[28:31]
	v_mfma_f32_16x16x32_bf16 v[56:59], v[186:189], v[152:155], v[56:59]
	v_mfma_f32_16x16x32_bf16 v[24:27], v[194:197], v[152:155], v[24:27]
	v_mfma_f32_16x16x32_bf16 v[52:55], v[186:189], v[160:163], v[52:55]
	v_mfma_f32_16x16x32_bf16 v[20:23], v[194:197], v[160:163], v[20:23]
	v_mfma_f32_16x16x32_bf16 v[48:51], v[186:189], v[178:181], v[48:51]
	v_mfma_f32_16x16x32_bf16 v[16:19], v[194:197], v[178:181], v[16:19]
	v_mfma_f32_16x16x32_bf16 v[60:63], v[190:193], v[148:151], v[60:63]
	v_mfma_f32_16x16x32_bf16 v[28:31], v[208:211], v[148:151], v[28:31]
	v_mfma_f32_16x16x32_bf16 v[56:59], v[190:193], v[156:159], v[56:59]
	v_mfma_f32_16x16x32_bf16 v[24:27], v[208:211], v[156:159], v[24:27]
	v_mfma_f32_16x16x32_bf16 v[52:55], v[190:193], v[174:177], v[52:55]
	v_mfma_f32_16x16x32_bf16 v[20:23], v[208:211], v[174:177], v[20:23]
	v_mfma_f32_16x16x32_bf16 v[48:51], v[190:193], v[182:185], v[48:51]
	v_mfma_f32_16x16x32_bf16 v[16:19], v[208:211], v[182:185], v[16:19]
	s_mov_b32 m0, s47
	v_lshl_add_u64 v[204:205], v[214:215], 0, s[0:1]
	s_barrier
	ds_read_b128 v[144:147], v199 offset:49152
	ds_read_b128 v[148:151], v199 offset:50176
	ds_read_b128 v[152:155], v199 offset:51200
	ds_read_b128 v[156:159], v199 offset:52224
	ds_read_b128 v[160:163], v199 offset:53248
	ds_read_b128 v[174:177], v199 offset:54272
	ds_read_b128 v[178:181], v199 offset:55296
	ds_read_b128 v[182:185], v199 offset:56320
	global_load_lds_dwordx4 v[204:205], off
	v_lshl_add_u64 v[204:205], v[216:217], 0, s[0:1]
	s_mov_b32 m0, s48
	s_nop 0
	global_load_lds_dwordx4 v[204:205], off
	s_barrier
; #define WAIT_V(n) asm volatile("s_waitcnt vmcnt(" #n ")" ::: "memory")
; #define WAIT_L(n) asm volatile("s_waitcnt lgkmcnt(" #n ")" ::: "memory")
; #define BAR __builtin_amdgcn_s_barrier()
; #define SCHED __builtin_amdgcn_sched_barrier(0)
; #define EPI_DONE do { } while (0)
; template <class Get, class Epi>
; DI void gemm_stream(LAS unsigned char* lds, const int K, const int ld, Get get, Epi epi) {
;     ...
;             LDA(At, 1, 1); STAGE(SAo(1, 0), a3);
;             BAR; WAIT_L(0); MMA(1, 0, At, B0); BAR; SCHED;
;             STAGE(SBo(1, 1), b3 + hstep);
;             WAIT_V(6); BAR; MMA(1, 1, At, B1); BAR;
; DI void epi_resid(const Acc& acc, const P& p, int brow, int bcol, int layer, int gch, bool from_input) {
;     EPI_IDX
;     const float* gate = modv(p, layer, brow, gch);
; #pragma unroll
;     for (int bj = 0; bj < 2; ++bj)
; #pragma unroll
;         for (int n = 0; n < 2; ++n) {
;             const int c0 = bcol + bj * 128 + wc * 32 + n * 16 + fq * 4;
;             const f32x4 g = *(const f32x4*)(gate + c0);
;             f32x4 xv[2][4];
; #pragma unroll
;             for (int ai = 0; ai < 2; ++ai)
; #pragma unroll
;                 for (int m = 0; m < 4; ++m) {
;                     const int r = brow + ai * 128 + wr * 64 + m * 16 + fr;
;                     const float* sp = (from_input ? inrow(p, r) : xrow(p, r)) + c0;
;                     xv[ai][m] = *(const f32x4*)sp;
;                 }
;             __builtin_amdgcn_sched_barrier(0);
; #pragma unroll
;             for (int ai = 0; ai < 2; ++ai)
; #pragma unroll
;                 for (int m = 0; m < 4; ++m) {
;                     const int r = brow + ai * 128 + wr * 64 + m * 16 + fr;
;                     *(f32x4*)(xrow(p, r) + c0) = xv[ai][m] + g * acc[ai][bj][m][n];
;                 }
;             __builtin_amdgcn_sched_barrier(0);
;         }
;     EPI_DONE;
; }
	s_waitcnt lgkmcnt(0)
	v_mfma_f32_16x16x32_bf16 v[108:111], v[128:131], v[144:147], v[108:111]
	v_mfma_f32_16x16x32_bf16 v[76:79], v[136:139], v[144:147], v[76:79]
	v_mfma_f32_16x16x32_bf16 v[104:107], v[128:131], v[152:155], v[104:107]
	v_mfma_f32_16x16x32_bf16 v[72:75], v[136:139], v[152:155], v[72:75]
	v_mfma_f32_16x16x32_bf16 v[100:103], v[128:131], v[160:163], v[100:103]
	v_mfma_f32_16x16x32_bf16 v[68:71], v[136:139], v[160:163], v[68:71]
	v_mfma_f32_16x16x32_bf16 v[96:99], v[128:131], v[178:181], v[96:99]
	v_mfma_f32_16x16x32_bf16 v[64:67], v[136:139], v[178:181], v[64:67]
	v_mfma_f32_16x16x32_bf16 v[108:111], v[132:135], v[148:151], v[108:111]
	v_mfma_f32_16x16x32_bf16 v[76:79], v[140:143], v[148:151], v[76:79]
	v_mfma_f32_16x16x32_bf16 v[104:107], v[132:135], v[156:159], v[104:107]
	v_mfma_f32_16x16x32_bf16 v[72:75], v[140:143], v[156:159], v[72:75]
	v_mfma_f32_16x16x32_bf16 v[100:103], v[132:135], v[174:177], v[100:103]
	v_mfma_f32_16x16x32_bf16 v[68:71], v[140:143], v[174:177], v[68:71]
	v_mfma_f32_16x16x32_bf16 v[96:99], v[132:135], v[182:185], v[96:99]
	v_mfma_f32_16x16x32_bf16 v[64:67], v[140:143], v[182:185], v[64:67]
	s_barrier
	s_add_u32 s6, s10, 0x100080
	s_addc_u32 s7, s11, 0
	s_mov_b32 m0, s68
	v_lshl_add_u64 v[128:129], s[6:7], 0, v[164:165]
	global_load_lds_dwordx4 v[128:129], off
	v_lshl_add_u64 v[128:129], s[6:7], 0, v[166:167]
	s_mov_b32 m0, s69
	s_nop 0
	global_load_lds_dwordx4 v[128:129], off
	s_waitcnt vmcnt(6)
	s_barrier
	v_mfma_f32_16x16x32_bf16 v[44:47], v[186:189], v[144:147], v[44:47]
	v_mfma_f32_16x16x32_bf16 v[12:15], v[194:197], v[144:147], v[12:15]
	v_mfma_f32_16x16x32_bf16 v[40:43], v[186:189], v[152:155], v[40:43]
	v_mfma_f32_16x16x32_bf16 v[8:11], v[194:197], v[152:155], v[8:11]
	v_mfma_f32_16x16x32_bf16 v[36:39], v[186:189], v[160:163], v[36:39]
	v_mfma_f32_16x16x32_bf16 v[4:7], v[194:197], v[160:163], v[4:7]
	v_mfma_f32_16x16x32_bf16 v[32:35], v[186:189], v[178:181], v[32:35]
	v_mfma_f32_16x16x32_bf16 v[0:3], v[194:197], v[178:181], v[0:3]
	v_mfma_f32_16x16x32_bf16 v[44:47], v[190:193], v[148:151], v[44:47]
	v_mfma_f32_16x16x32_bf16 v[12:15], v[208:211], v[148:151], v[12:15]
	v_mfma_f32_16x16x32_bf16 v[40:43], v[190:193], v[156:159], v[40:43]
	v_mfma_f32_16x16x32_bf16 v[8:11], v[208:211], v[156:159], v[8:11]
	v_mfma_f32_16x16x32_bf16 v[36:39], v[190:193], v[174:177], v[36:39]
	v_mfma_f32_16x16x32_bf16 v[4:7], v[208:211], v[174:177], v[4:7]
	v_mfma_f32_16x16x32_bf16 v[32:35], v[190:193], v[182:185], v[32:35]
	v_mfma_f32_16x16x32_bf16 v[0:3], v[208:211], v[182:185], v[0:3]
	s_add_i32 s16, s16, 2
	s_add_u32 s14, s14, 0x100
	s_addc_u32 s15, s15, 0
	s_cmp_gt_u32 s16, 61
	s_mov_b64 s[6:7], s[8:9]
	s_barrier
	s_cbranch_scc0 .LBB0_2670
	s_lshl_b32 s12, s3, 21
	s_lshl_b32 s13, s2, 10
	s_lshr_b32 s16, s3, 4
	s_add_u32 s12, s12, s13
	s_mul_i32 s16, s16, 6
	s_add_i32 s16, s16, 32
	s_lshl_b32 s16, s16, 13
	s_add_u32 s16, s16, s13
	s_add_u32 s10, s26, s16
	s_addc_u32 s11, s27, 0
	s_add_u32 s6, s24, s12
	s_addc_u32 s7, s25, 0
	v_lshrrev_b32_e32 v224, 6, v206
	v_and_b32_e32 v225, 3, v224
	v_lshrrev_b32_e32 v224, 2, v224
	v_and_b32_e32 v205, 15, v206
	v_bfe_u32 v226, v206, 4, 2
	v_lshl_add_u32 v225, v225, 3, v226
	v_lshl_add_u32 v224, v224, 6, v205
	v_lshlrev_b32_e32 v205, 4, v225
	v_lshl_add_u32 v203, v224, 13, v205
	v_mov_b32_e32 v204, v203
	global_load_dwordx4 v[128:131], v205, s[10:11] offset:0
	global_load_dwordx4 v[132:135], v205, s[10:11] offset:64
	global_load_dwordx4 v[136:139], v205, s[10:11] offset:512
	global_load_dwordx4 v[140:143], v205, s[10:11] offset:576
	global_load_dwordx4 v[144:147], v203, s[6:7] offset:0
	global_load_dwordx4 v[148:151], v203, s[6:7] offset:64
	global_load_dwordx4 v[152:155], v203, s[6:7] offset:512
	global_load_dwordx4 v[156:159], v203, s[6:7] offset:576
	v_add_u32_e32 v203, 0x20000, v203
	global_load_dwordx4 v[160:163], v203, s[6:7] offset:0
	global_load_dwordx4 v[174:177], v203, s[6:7] offset:64
	global_load_dwordx4 v[178:181], v203, s[6:7] offset:512
	global_load_dwordx4 v[182:185], v203, s[6:7] offset:576
	v_add_u32_e32 v203, 0x20000, v203
	global_load_dwordx4 v[186:189], v203, s[6:7] offset:0
	global_load_dwordx4 v[190:193], v203, s[6:7] offset:64
	global_load_dwordx4 v[194:197], v203, s[6:7] offset:512
	global_load_dwordx4 v[208:211], v203, s[6:7] offset:576
	v_add_u32_e32 v203, 0x20000, v203
	global_load_dwordx4 v[212:215], v203, s[6:7] offset:0
	global_load_dwordx4 v[216:219], v203, s[6:7] offset:64
	global_load_dwordx4 v[220:223], v203, s[6:7] offset:512
	global_load_dwordx4 v[224:227], v203, s[6:7] offset:576
	v_add_u32_e32 v203, 0xa0000, v203
	s_waitcnt vmcnt(12)
	v_pk_fma_f32 v[124:125], v[124:125], v[128:129], v[144:145]
	v_pk_fma_f32 v[126:127], v[126:127], v[130:131], v[146:147]
	v_pk_fma_f32 v[92:93], v[92:93], v[132:133], v[148:149]
	v_pk_fma_f32 v[94:95], v[94:95], v[134:135], v[150:151]
	v_pk_fma_f32 v[60:61], v[60:61], v[136:137], v[152:153]
	v_pk_fma_f32 v[62:63], v[62:63], v[138:139], v[154:155]
	v_pk_fma_f32 v[28:29], v[28:29], v[140:141], v[156:157]
	v_pk_fma_f32 v[30:31], v[30:31], v[142:143], v[158:159]
	global_store_dwordx4 v204, v[124:127], s[6:7] offset:0
	global_store_dwordx4 v204, v[92:95], s[6:7] offset:64
	global_store_dwordx4 v204, v[60:63], s[6:7] offset:512
	global_store_dwordx4 v204, v[28:31], s[6:7] offset:576
	v_add_u32_e32 v204, 0x20000, v204
	global_load_dwordx4 v[144:147], v203, s[6:7] offset:0
	global_load_dwordx4 v[148:151], v203, s[6:7] offset:64
	global_load_dwordx4 v[152:155], v203, s[6:7] offset:512
	global_load_dwordx4 v[156:159], v203, s[6:7] offset:576
	v_add_u32_e32 v203, 0x20000, v203
	s_waitcnt vmcnt(16)
; DI void epi_resid(const Acc& acc, const P& p, int brow, int bcol, int layer, int gch, bool from_input) {
;     ...
;             for (int ai = 0; ai < 2; ++ai)
; #pragma unroll
;                 for (int m = 0; m < 4; ++m) {
;                     const int r = brow + ai * 128 + wr * 64 + m * 16 + fr;
;                     *(f32x4*)(xrow(p, r) + c0) = xv[ai][m] + g * acc[ai][bj][m][n];
;                 }
	v_pk_fma_f32 v[120:121], v[120:121], v[128:129], v[160:161]
	v_pk_fma_f32 v[122:123], v[122:123], v[130:131], v[162:163]
	v_pk_fma_f32 v[88:89], v[88:89], v[132:133], v[174:175]
	v_pk_fma_f32 v[90:91], v[90:91], v[134:135], v[176:177]
	v_pk_fma_f32 v[56:57], v[56:57], v[136:137], v[178:179]
	v_pk_fma_f32 v[58:59], v[58:59], v[138:139], v[180:181]
	v_pk_fma_f32 v[24:25], v[24:25], v[140:141], v[182:183]
	v_pk_fma_f32 v[26:27], v[26:27], v[142:143], v[184:185]
	global_store_dwordx4 v204, v[120:123], s[6:7] offset:0
	global_store_dwordx4 v204, v[88:91], s[6:7] offset:64
	global_store_dwordx4 v204, v[56:59], s[6:7] offset:512
	global_store_dwordx4 v204, v[24:27], s[6:7] offset:576
	v_add_u32_e32 v204, 0x20000, v204
	global_load_dwordx4 v[160:163], v203, s[6:7] offset:0
	global_load_dwordx4 v[174:177], v203, s[6:7] offset:64
	global_load_dwordx4 v[178:181], v203, s[6:7] offset:512
	global_load_dwordx4 v[182:185], v203, s[6:7] offset:576
	v_add_u32_e32 v203, 0x20000, v203
	s_waitcnt vmcnt(20)
	v_pk_fma_f32 v[116:117], v[116:117], v[128:129], v[186:187]
	v_pk_fma_f32 v[118:119], v[118:119], v[130:131], v[188:189]
	v_pk_fma_f32 v[84:85], v[84:85], v[132:133], v[190:191]
	v_pk_fma_f32 v[86:87], v[86:87], v[134:135], v[192:193]
	v_pk_fma_f32 v[52:53], v[52:53], v[136:137], v[194:195]
	v_pk_fma_f32 v[54:55], v[54:55], v[138:139], v[196:197]
	v_pk_fma_f32 v[20:21], v[20:21], v[140:141], v[208:209]
	v_pk_fma_f32 v[22:23], v[22:23], v[142:143], v[210:211]
	global_store_dwordx4 v204, v[116:119], s[6:7] offset:0
	global_store_dwordx4 v204, v[84:87], s[6:7] offset:64
	global_store_dwordx4 v204, v[52:55], s[6:7] offset:512
	global_store_dwordx4 v204, v[20:23], s[6:7] offset:576
	v_add_u32_e32 v204, 0x20000, v204
	global_load_dwordx4 v[186:189], v203, s[6:7] offset:0
	global_load_dwordx4 v[190:193], v203, s[6:7] offset:64
	global_load_dwordx4 v[194:197], v203, s[6:7] offset:512
	global_load_dwordx4 v[208:211], v203, s[6:7] offset:576
	v_add_u32_e32 v203, 0x20000, v203
	s_waitcnt vmcnt(24)
	v_pk_fma_f32 v[112:113], v[112:113], v[128:129], v[212:213]
	v_pk_fma_f32 v[114:115], v[114:115], v[130:131], v[214:215]
	v_pk_fma_f32 v[80:81], v[80:81], v[132:133], v[216:217]
	v_pk_fma_f32 v[82:83], v[82:83], v[134:135], v[218:219]
	v_pk_fma_f32 v[48:49], v[48:49], v[136:137], v[220:221]
	v_pk_fma_f32 v[50:51], v[50:51], v[138:139], v[222:223]
	v_pk_fma_f32 v[16:17], v[16:17], v[140:141], v[224:225]
	v_pk_fma_f32 v[18:19], v[18:19], v[142:143], v[226:227]
	global_store_dwordx4 v204, v[112:115], s[6:7] offset:0
	global_store_dwordx4 v204, v[80:83], s[6:7] offset:64
	global_store_dwordx4 v204, v[48:51], s[6:7] offset:512
	global_store_dwordx4 v204, v[16:19], s[6:7] offset:576
	v_add_u32_e32 v204, 0xa0000, v204
	global_load_dwordx4 v[212:215], v203, s[6:7] offset:0
	global_load_dwordx4 v[216:219], v203, s[6:7] offset:64
	global_load_dwordx4 v[220:223], v203, s[6:7] offset:512
	global_load_dwordx4 v[224:227], v203, s[6:7] offset:576
	s_waitcnt vmcnt(24)
	v_pk_fma_f32 v[108:109], v[108:109], v[128:129], v[144:145]
	v_pk_fma_f32 v[110:111], v[110:111], v[130:131], v[146:147]
	v_pk_fma_f32 v[76:77], v[76:77], v[132:133], v[148:149]
	v_pk_fma_f32 v[78:79], v[78:79], v[134:135], v[150:151]
	v_pk_fma_f32 v[44:45], v[44:45], v[136:137], v[152:153]
	v_pk_fma_f32 v[46:47], v[46:47], v[138:139], v[154:155]
	v_pk_fma_f32 v[12:13], v[12:13], v[140:141], v[156:157]
	v_pk_fma_f32 v[14:15], v[14:15], v[142:143], v[158:159]
	global_store_dwordx4 v204, v[108:111], s[6:7] offset:0
	global_store_dwordx4 v204, v[76:79], s[6:7] offset:64
	global_store_dwordx4 v204, v[44:47], s[6:7] offset:512
	global_store_dwordx4 v204, v[12:15], s[6:7] offset:576
	v_add_u32_e32 v204, 0x20000, v204
	s_waitcnt vmcnt(20)
	v_pk_fma_f32 v[104:105], v[104:105], v[128:129], v[160:161]
	v_pk_fma_f32 v[106:107], v[106:107], v[130:131], v[162:163]
	v_pk_fma_f32 v[72:73], v[72:73], v[132:133], v[174:175]
	v_pk_fma_f32 v[74:75], v[74:75], v[134:135], v[176:177]
	v_pk_fma_f32 v[40:41], v[40:41], v[136:137], v[178:179]
	v_pk_fma_f32 v[42:43], v[42:43], v[138:139], v[180:181]
	v_pk_fma_f32 v[8:9], v[8:9], v[140:141], v[182:183]
	v_pk_fma_f32 v[10:11], v[10:11], v[142:143], v[184:185]
	global_store_dwordx4 v204, v[104:107], s[6:7] offset:0
	global_store_dwordx4 v204, v[72:75], s[6:7] offset:64
	global_store_dwordx4 v204, v[40:43], s[6:7] offset:512
	global_store_dwordx4 v204, v[8:11], s[6:7] offset:576
	v_add_u32_e32 v204, 0x20000, v204
	s_waitcnt vmcnt(16)
	v_pk_fma_f32 v[100:101], v[100:101], v[128:129], v[186:187]
	v_pk_fma_f32 v[102:103], v[102:103], v[130:131], v[188:189]
	v_pk_fma_f32 v[68:69], v[68:69], v[132:133], v[190:191]
	v_pk_fma_f32 v[70:71], v[70:71], v[134:135], v[192:193]
	v_pk_fma_f32 v[36:37], v[36:37], v[136:137], v[194:195]
	v_pk_fma_f32 v[38:39], v[38:39], v[138:139], v[196:197]
	v_pk_fma_f32 v[4:5], v[4:5], v[140:141], v[208:209]
	v_pk_fma_f32 v[6:7], v[6:7], v[142:143], v[210:211]
	global_store_dwordx4 v204, v[100:103], s[6:7] offset:0
	global_store_dwordx4 v204, v[68:71], s[6:7] offset:64
	global_store_dwordx4 v204, v[36:39], s[6:7] offset:512
	global_store_dwordx4 v204, v[4:7], s[6:7] offset:576
	v_add_u32_e32 v204, 0x20000, v204
	s_waitcnt vmcnt(12)
	v_pk_fma_f32 v[96:97], v[96:97], v[128:129], v[212:213]
	v_pk_fma_f32 v[98:99], v[98:99], v[130:131], v[214:215]
	v_pk_fma_f32 v[64:65], v[64:65], v[132:133], v[216:217]
	v_pk_fma_f32 v[66:67], v[66:67], v[134:135], v[218:219]
	v_pk_fma_f32 v[32:33], v[32:33], v[136:137], v[220:221]
	v_pk_fma_f32 v[34:35], v[34:35], v[138:139], v[222:223]
	v_pk_fma_f32 v[0:1], v[0:1], v[140:141], v[224:225]
	v_pk_fma_f32 v[2:3], v[2:3], v[142:143], v[226:227]
	global_store_dwordx4 v204, v[96:99], s[6:7] offset:0
	global_store_dwordx4 v204, v[64:67], s[6:7] offset:64
	global_store_dwordx4 v204, v[32:35], s[6:7] offset:512
	global_store_dwordx4 v204, v[0:3], s[6:7] offset:576
	s_branch .Lresid_latch_wout1

; template <class Get, class Epi>
; DI void gemm_stream(LAS unsigned char* lds, const int K, const int ld, Get get, Epi epi) {
;     ...
;         epi(acc, cur);
;         if (!has_next) break;
;         ZERO_ACC;
;         cur = nxt; cA = nA; cB = nB; ++ui;
.LBB0_3109:
.Lresid_latch_ffndL1:
	s_and_b64 vcc, exec, s[2:3]
	s_mov_b32 s12, s60
	s_mov_b32 s13, s61
	s_mov_b64 s[6:7], s[38:39]
	s_mov_b64 s[4:5], s[36:37]
	s_cbranch_vccnz .LBB0_3370

; #define WAIT_V(n) asm volatile("s_waitcnt vmcnt(" #n ")" ::: "memory")
; #define WAIT_L(n) asm volatile("s_waitcnt lgkmcnt(" #n ")" ::: "memory")
; #define BAR __builtin_amdgcn_s_barrier()
; #define SCHED __builtin_amdgcn_sched_barrier(0)
; template <class Get, class Epi>
; DI void gemm_stream(LAS unsigned char* lds, const int K, const int ld, Get get, Epi epi) {
;     ...
;             LDB(B0, 0, 0); SCHED; LDA(At, 0, 0); STAGE(SAo(1, 1), a1 + hstep);
;             WAIT_L(8); BAR; WAIT_L(0); MMA(0, 0, At, B0); BAR; SCHED;
;             LDB(B1, 0, 1); STAGE(SBo(0, 0), b2);
;             BAR; WAIT_L(0); MMA(0, 1, At, B1); BAR;
;             LDA(At, 0, 1); STAGE(SAo(0, 0), a2);
;             BAR; WAIT_L(0); MMA(1, 0, At, B0); BAR; SCHED;
;             STAGE(SBo(0, 1), b2 + hstep);
;             WAIT_V(6); BAR; MMA(1, 1, At, B1); BAR;
;             LDB(B0, 1, 0); SCHED; LDA(At, 1, 0); STAGE(SAo(0, 1), a2 + hstep);
;             WAIT_L(8); BAR; WAIT_L(0); MMA(0, 0, At, B0); BAR; SCHED;
;             LDB(B1, 1, 1); STAGE(SBo(1, 0), b3);
;             BAR; WAIT_L(0); MMA(0, 1, At, B1); BAR;
.LBB0_3113:
	ds_read_b128 v[128:131], v199
	ds_read_b128 v[132:135], v199 offset:1024
	ds_read_b128 v[136:139], v199 offset:2048
	ds_read_b128 v[140:143], v199 offset:3072
	s_add_u32 s6, s4, 0x100
	s_addc_u32 s7, s5, 0
	s_cmpk_eq_i32 s16, 0x54
	s_cselect_b32 s11, s37, s7
	s_cselect_b32 s10, s36, s6
	s_cselect_b32 s9, s39, s15
	s_cselect_b32 s8, s38, s14
	s_mov_b32 m0, s54
	v_lshl_add_u64 v[186:187], s[4:5], 0, v[168:169]
	ds_read_b128 v[144:147], v200
	ds_read_b128 v[148:151], v200 offset:1024
	ds_read_b128 v[152:155], v200 offset:2048
	ds_read_b128 v[156:159], v200 offset:3072
	ds_read_b128 v[160:163], v200 offset:4096
	ds_read_b128 v[174:177], v200 offset:5120
	ds_read_b128 v[178:181], v200 offset:6144
	ds_read_b128 v[182:185], v200 offset:7168
	global_load_lds_dwordx4 v[186:187], off
	v_lshl_add_u64 v[186:187], s[4:5], 0, v[170:171]
	s_mov_b32 m0, s55
	s_nop 0
	global_load_lds_dwordx4 v[186:187], off
	s_waitcnt lgkmcnt(8)
	s_barrier
	s_waitcnt lgkmcnt(0)
	v_mfma_f32_16x16x32_bf16 v[124:127], v[128:131], v[144:147], v[124:127]
	v_mfma_f32_16x16x32_bf16 v[92:95], v[136:139], v[144:147], v[92:95]
	v_mfma_f32_16x16x32_bf16 v[120:123], v[128:131], v[152:155], v[120:123]
	v_mfma_f32_16x16x32_bf16 v[88:91], v[136:139], v[152:155], v[88:91]
	v_mfma_f32_16x16x32_bf16 v[116:119], v[128:131], v[160:163], v[116:119]
	v_mfma_f32_16x16x32_bf16 v[84:87], v[136:139], v[160:163], v[84:87]
	v_mfma_f32_16x16x32_bf16 v[112:115], v[128:131], v[178:181], v[112:115]
	v_mfma_f32_16x16x32_bf16 v[80:83], v[136:139], v[178:181], v[80:83]
	v_mfma_f32_16x16x32_bf16 v[124:127], v[132:135], v[148:151], v[124:127]
	v_mfma_f32_16x16x32_bf16 v[92:95], v[140:143], v[148:151], v[92:95]
	v_mfma_f32_16x16x32_bf16 v[120:123], v[132:135], v[156:159], v[120:123]
	v_mfma_f32_16x16x32_bf16 v[88:91], v[140:143], v[156:159], v[88:91]
	v_mfma_f32_16x16x32_bf16 v[116:119], v[132:135], v[174:177], v[116:119]
	v_mfma_f32_16x16x32_bf16 v[84:87], v[140:143], v[174:177], v[84:87]
	v_mfma_f32_16x16x32_bf16 v[112:115], v[132:135], v[182:185], v[112:115]
	v_mfma_f32_16x16x32_bf16 v[80:83], v[140:143], v[182:185], v[80:83]
	s_barrier
	s_mov_b32 m0, s56
	v_lshl_add_u64 v[208:209], s[8:9], 0, v[164:165]
	ds_read_b128 v[186:189], v201
	ds_read_b128 v[190:193], v201 offset:1024
	ds_read_b128 v[194:197], v201 offset:2048
	ds_read_b128 v[202:205], v201 offset:3072
	global_load_lds_dwordx4 v[208:209], off
	v_lshl_add_u64 v[210:211], s[8:9], 0, v[166:167]
	s_mov_b32 m0, s57
	s_nop 0
	global_load_lds_dwordx4 v[210:211], off
	s_barrier
	s_waitcnt lgkmcnt(0)
	v_mfma_f32_16x16x32_bf16 v[60:63], v[186:189], v[144:147], v[60:63]
	v_mfma_f32_16x16x32_bf16 v[28:31], v[194:197], v[144:147], v[28:31]
	v_mfma_f32_16x16x32_bf16 v[56:59], v[186:189], v[152:155], v[56:59]
	v_mfma_f32_16x16x32_bf16 v[24:27], v[194:197], v[152:155], v[24:27]
	v_mfma_f32_16x16x32_bf16 v[52:55], v[186:189], v[160:163], v[52:55]
	v_mfma_f32_16x16x32_bf16 v[20:23], v[194:197], v[160:163], v[20:23]
	v_mfma_f32_16x16x32_bf16 v[48:51], v[186:189], v[178:181], v[48:51]
	v_mfma_f32_16x16x32_bf16 v[16:19], v[194:197], v[178:181], v[16:19]
	v_mfma_f32_16x16x32_bf16 v[60:63], v[190:193], v[148:151], v[60:63]
	v_mfma_f32_16x16x32_bf16 v[28:31], v[202:205], v[148:151], v[28:31]
	v_mfma_f32_16x16x32_bf16 v[56:59], v[190:193], v[156:159], v[56:59]
	v_mfma_f32_16x16x32_bf16 v[24:27], v[202:205], v[156:159], v[24:27]
	v_mfma_f32_16x16x32_bf16 v[52:55], v[190:193], v[174:177], v[52:55]
	v_mfma_f32_16x16x32_bf16 v[20:23], v[202:205], v[174:177], v[20:23]
	v_mfma_f32_16x16x32_bf16 v[48:51], v[190:193], v[182:185], v[48:51]
	v_mfma_f32_16x16x32_bf16 v[16:19], v[202:205], v[182:185], v[16:19]
	s_mov_b32 m0, s33
	v_lshl_add_u64 v[212:213], s[10:11], 0, v[164:165]
	s_barrier
	ds_read_b128 v[144:147], v200 offset:16384
	ds_read_b128 v[148:151], v200 offset:17408
	ds_read_b128 v[152:155], v200 offset:18432
	ds_read_b128 v[156:159], v200 offset:19456
	ds_read_b128 v[160:163], v200 offset:20480
	ds_read_b128 v[174:177], v200 offset:21504
	ds_read_b128 v[178:181], v200 offset:22528
	ds_read_b128 v[182:185], v200 offset:23552
	global_load_lds_dwordx4 v[212:213], off
	v_lshl_add_u64 v[214:215], s[10:11], 0, v[166:167]
	s_mov_b32 m0, s42
	s_nop 0
	global_load_lds_dwordx4 v[214:215], off
	s_barrier
	s_waitcnt lgkmcnt(0)
	v_mfma_f32_16x16x32_bf16 v[108:111], v[128:131], v[144:147], v[108:111]
	v_mfma_f32_16x16x32_bf16 v[76:79], v[136:139], v[144:147], v[76:79]
	v_mfma_f32_16x16x32_bf16 v[104:107], v[128:131], v[152:155], v[104:107]
	v_mfma_f32_16x16x32_bf16 v[72:75], v[136:139], v[152:155], v[72:75]
	v_mfma_f32_16x16x32_bf16 v[100:103], v[128:131], v[160:163], v[100:103]
	v_mfma_f32_16x16x32_bf16 v[68:71], v[136:139], v[160:163], v[68:71]
	v_mfma_f32_16x16x32_bf16 v[96:99], v[128:131], v[178:181], v[96:99]
	v_mfma_f32_16x16x32_bf16 v[64:67], v[136:139], v[178:181], v[64:67]
	v_mfma_f32_16x16x32_bf16 v[108:111], v[132:135], v[148:151], v[108:111]
	v_mfma_f32_16x16x32_bf16 v[76:79], v[140:143], v[148:151], v[76:79]
	v_mfma_f32_16x16x32_bf16 v[104:107], v[132:135], v[156:159], v[104:107]
	v_mfma_f32_16x16x32_bf16 v[72:75], v[140:143], v[156:159], v[72:75]
	v_mfma_f32_16x16x32_bf16 v[100:103], v[132:135], v[174:177], v[100:103]
	v_mfma_f32_16x16x32_bf16 v[68:71], v[140:143], v[174:177], v[68:71]
	v_mfma_f32_16x16x32_bf16 v[96:99], v[132:135], v[182:185], v[96:99]
	v_mfma_f32_16x16x32_bf16 v[64:67], v[140:143], v[182:185], v[64:67]
	s_barrier
	s_add_u32 s4, s8, 0x160000
	s_addc_u32 s5, s9, 0
	s_mov_b32 m0, s58
	v_lshl_add_u64 v[128:129], s[4:5], 0, v[164:165]
	global_load_lds_dwordx4 v[128:129], off
	v_lshl_add_u64 v[128:129], s[4:5], 0, v[166:167]
	s_mov_b32 m0, s59
	s_nop 0
	global_load_lds_dwordx4 v[128:129], off
	s_waitcnt vmcnt(6)
	s_barrier
; #define WAIT_V(n) asm volatile("s_waitcnt vmcnt(" #n ")" ::: "memory")
; #define WAIT_L(n) asm volatile("s_waitcnt lgkmcnt(" #n ")" ::: "memory")
; #define BAR __builtin_amdgcn_s_barrier()
; #define SCHED __builtin_amdgcn_sched_barrier(0)
; template <class Get, class Epi>
; DI void gemm_stream(LAS unsigned char* lds, const int K, const int ld, Get get, Epi epi) {
;     ...
;             LDB(B0, 1, 0); SCHED; LDA(At, 1, 0); STAGE(SAo(0, 1), a2 + hstep);
;             WAIT_L(8); BAR; WAIT_L(0); MMA(0, 0, At, B0); BAR; SCHED;
;             LDB(B1, 1, 1); STAGE(SBo(1, 0), b3);
;             BAR; WAIT_L(0); MMA(0, 1, At, B1); BAR;
;             LDA(At, 1, 1); STAGE(SAo(1, 0), a3);
;             BAR; WAIT_L(0); MMA(1, 0, At, B0); BAR; SCHED;
;             STAGE(SBo(1, 1), b3 + hstep);
;             WAIT_V(6); BAR; MMA(1, 1, At, B1); BAR;
	v_mfma_f32_16x16x32_bf16 v[44:47], v[186:189], v[144:147], v[44:47]
	v_mfma_f32_16x16x32_bf16 v[12:15], v[194:197], v[144:147], v[12:15]
	v_mfma_f32_16x16x32_bf16 v[40:43], v[186:189], v[152:155], v[40:43]
	v_mfma_f32_16x16x32_bf16 v[8:11], v[194:197], v[152:155], v[8:11]
	v_mfma_f32_16x16x32_bf16 v[36:39], v[186:189], v[160:163], v[36:39]
	v_mfma_f32_16x16x32_bf16 v[4:7], v[194:197], v[160:163], v[4:7]
	v_mfma_f32_16x16x32_bf16 v[32:35], v[186:189], v[178:181], v[32:35]
	v_mfma_f32_16x16x32_bf16 v[0:3], v[194:197], v[178:181], v[0:3]
	v_mfma_f32_16x16x32_bf16 v[44:47], v[190:193], v[148:151], v[44:47]
	v_mfma_f32_16x16x32_bf16 v[12:15], v[202:205], v[148:151], v[12:15]
	v_mfma_f32_16x16x32_bf16 v[40:43], v[190:193], v[156:159], v[40:43]
	v_mfma_f32_16x16x32_bf16 v[8:11], v[202:205], v[156:159], v[8:11]
	v_mfma_f32_16x16x32_bf16 v[36:39], v[190:193], v[174:177], v[36:39]
	v_mfma_f32_16x16x32_bf16 v[4:7], v[202:205], v[174:177], v[4:7]
	v_mfma_f32_16x16x32_bf16 v[32:35], v[190:193], v[182:185], v[32:35]
	v_mfma_f32_16x16x32_bf16 v[0:3], v[202:205], v[182:185], v[0:3]
	s_add_i32 s17, 16, 0x18000
	v_add_u32_e32 v140, s17, v198
	s_barrier
	ds_read_b128 v[128:131], v140
	ds_read_b128 v[132:135], v140 offset:1024
	ds_read_b128 v[136:139], v140 offset:2048
	ds_read_b128 v[140:143], v140 offset:3072
	s_add_u32 s4, s10, 0x160000
	s_addc_u32 s5, s11, 0
	s_mov_b32 m0, s43
	v_lshl_add_u64 v[186:187], s[4:5], 0, v[164:165]
	ds_read_b128 v[144:147], v200 offset:32768
	ds_read_b128 v[148:151], v200 offset:33792
	ds_read_b128 v[152:155], v200 offset:34816
	ds_read_b128 v[156:159], v200 offset:35840
	ds_read_b128 v[160:163], v200 offset:36864
	ds_read_b128 v[174:177], v200 offset:37888
	ds_read_b128 v[178:181], v200 offset:38912
	ds_read_b128 v[182:185], v200 offset:39936
	global_load_lds_dwordx4 v[186:187], off
	v_lshl_add_u64 v[186:187], s[4:5], 0, v[166:167]
	s_mov_b32 m0, s44
	s_nop 0
	global_load_lds_dwordx4 v[186:187], off
	s_waitcnt lgkmcnt(8)
	s_barrier
	s_waitcnt lgkmcnt(0)
	v_mfma_f32_16x16x32_bf16 v[124:127], v[128:131], v[144:147], v[124:127]
	v_mfma_f32_16x16x32_bf16 v[92:95], v[136:139], v[144:147], v[92:95]
	v_mfma_f32_16x16x32_bf16 v[120:123], v[128:131], v[152:155], v[120:123]
	v_mfma_f32_16x16x32_bf16 v[88:91], v[136:139], v[152:155], v[88:91]
	v_mfma_f32_16x16x32_bf16 v[116:119], v[128:131], v[160:163], v[116:119]
	v_mfma_f32_16x16x32_bf16 v[84:87], v[136:139], v[160:163], v[84:87]
	v_mfma_f32_16x16x32_bf16 v[112:115], v[128:131], v[178:181], v[112:115]
	v_mfma_f32_16x16x32_bf16 v[80:83], v[136:139], v[178:181], v[80:83]
	v_mfma_f32_16x16x32_bf16 v[124:127], v[132:135], v[148:151], v[124:127]
	v_mfma_f32_16x16x32_bf16 v[92:95], v[140:143], v[148:151], v[92:95]
	v_mfma_f32_16x16x32_bf16 v[120:123], v[132:135], v[156:159], v[120:123]
	v_mfma_f32_16x16x32_bf16 v[88:91], v[140:143], v[156:159], v[88:91]
	v_mfma_f32_16x16x32_bf16 v[116:119], v[132:135], v[174:177], v[116:119]
	v_mfma_f32_16x16x32_bf16 v[84:87], v[140:143], v[174:177], v[84:87]
	v_mfma_f32_16x16x32_bf16 v[112:115], v[132:135], v[182:185], v[112:115]
	v_mfma_f32_16x16x32_bf16 v[80:83], v[140:143], v[182:185], v[80:83]
	s_barrier
	s_add_i32 s10, 16, 0x1c000
	s_add_i32 s4, s17, s21
	v_add_u32_e32 v202, s10, v198
	v_lshl_add_u64 v[208:209], v[208:209], 0, s[0:1]
	s_mov_b32 m0, s4
	ds_read_b128 v[186:189], v202
	ds_read_b128 v[190:193], v202 offset:1024
	ds_read_b128 v[194:197], v202 offset:2048
	ds_read_b128 v[202:205], v202 offset:3072
	global_load_lds_dwordx4 v[208:209], off
	v_lshl_add_u64 v[208:209], v[210:211], 0, s[0:1]
	s_add_i32 m0, s4, 0x2000
	s_nop 0
	global_load_lds_dwordx4 v[208:209], off
	s_barrier
	s_waitcnt lgkmcnt(0)
	v_mfma_f32_16x16x32_bf16 v[60:63], v[186:189], v[144:147], v[60:63]
	v_mfma_f32_16x16x32_bf16 v[28:31], v[194:197], v[144:147], v[28:31]
	v_mfma_f32_16x16x32_bf16 v[56:59], v[186:189], v[152:155], v[56:59]
	v_mfma_f32_16x16x32_bf16 v[24:27], v[194:197], v[152:155], v[24:27]
	v_mfma_f32_16x16x32_bf16 v[52:55], v[186:189], v[160:163], v[52:55]
	v_mfma_f32_16x16x32_bf16 v[20:23], v[194:197], v[160:163], v[20:23]
	v_mfma_f32_16x16x32_bf16 v[48:51], v[186:189], v[178:181], v[48:51]
	v_mfma_f32_16x16x32_bf16 v[16:19], v[194:197], v[178:181], v[16:19]
	v_mfma_f32_16x16x32_bf16 v[60:63], v[190:193], v[148:151], v[60:63]
	v_mfma_f32_16x16x32_bf16 v[28:31], v[202:205], v[148:151], v[28:31]
	v_mfma_f32_16x16x32_bf16 v[56:59], v[190:193], v[156:159], v[56:59]
	v_mfma_f32_16x16x32_bf16 v[24:27], v[202:205], v[156:159], v[24:27]
	v_mfma_f32_16x16x32_bf16 v[52:55], v[190:193], v[174:177], v[52:55]
	v_mfma_f32_16x16x32_bf16 v[20:23], v[202:205], v[174:177], v[20:23]
	v_mfma_f32_16x16x32_bf16 v[48:51], v[190:193], v[182:185], v[48:51]
	v_mfma_f32_16x16x32_bf16 v[16:19], v[202:205], v[182:185], v[16:19]
	s_mov_b32 m0, s45
	v_lshl_add_u64 v[208:209], v[212:213], 0, s[0:1]
	s_barrier
	ds_read_b128 v[144:147], v200 offset:49152
	ds_read_b128 v[148:151], v200 offset:50176
	ds_read_b128 v[152:155], v200 offset:51200
	ds_read_b128 v[156:159], v200 offset:52224
	ds_read_b128 v[160:163], v200 offset:53248
	ds_read_b128 v[174:177], v200 offset:54272
	ds_read_b128 v[178:181], v200 offset:55296
	ds_read_b128 v[182:185], v200 offset:56320
	global_load_lds_dwordx4 v[208:209], off
	v_lshl_add_u64 v[208:209], v[214:215], 0, s[0:1]
	s_mov_b32 m0, s46
	s_nop 0
	global_load_lds_dwordx4 v[208:209], off
	s_barrier
; #define WAIT_V(n) asm volatile("s_waitcnt vmcnt(" #n ")" ::: "memory")
; #define WAIT_L(n) asm volatile("s_waitcnt lgkmcnt(" #n ")" ::: "memory")
; #define BAR __builtin_amdgcn_s_barrier()
; #define SCHED __builtin_amdgcn_sched_barrier(0)
; #define EPI_DONE do { } while (0)
; template <class Get, class Epi>
; DI void gemm_stream(LAS unsigned char* lds, const int K, const int ld, Get get, Epi epi) {
;     ...
;             LDA(At, 1, 1); STAGE(SAo(1, 0), a3);
;             BAR; WAIT_L(0); MMA(1, 0, At, B0); BAR; SCHED;
;             STAGE(SBo(1, 1), b3 + hstep);
;             WAIT_V(6); BAR; MMA(1, 1, At, B1); BAR;
; DI void epi_resid(const Acc& acc, const P& p, int brow, int bcol, int layer, int gch, bool from_input) {
;     EPI_IDX
;     const float* gate = modv(p, layer, brow, gch);
; #pragma unroll
;     for (int bj = 0; bj < 2; ++bj)
; #pragma unroll
;         for (int n = 0; n < 2; ++n) {
;             const int c0 = bcol + bj * 128 + wc * 32 + n * 16 + fq * 4;
;             const f32x4 g = *(const f32x4*)(gate + c0);
;             f32x4 xv[2][4];
; #pragma unroll
;             for (int ai = 0; ai < 2; ++ai)
; #pragma unroll
;                 for (int m = 0; m < 4; ++m) {
;                     const int r = brow + ai * 128 + wr * 64 + m * 16 + fr;
;                     const float* sp = (from_input ? inrow(p, r) : xrow(p, r)) + c0;
;                     xv[ai][m] = *(const f32x4*)sp;
;                 }
;             __builtin_amdgcn_sched_barrier(0);
; #pragma unroll
;             for (int ai = 0; ai < 2; ++ai)
; #pragma unroll
;                 for (int m = 0; m < 4; ++m) {
;                     const int r = brow + ai * 128 + wr * 64 + m * 16 + fr;
;                     *(f32x4*)(xrow(p, r) + c0) = xv[ai][m] + g * acc[ai][bj][m][n];
;                 }
;             __builtin_amdgcn_sched_barrier(0);
;         }
;     EPI_DONE;
; }
	s_waitcnt lgkmcnt(0)
	v_mfma_f32_16x16x32_bf16 v[108:111], v[128:131], v[144:147], v[108:111]
	v_mfma_f32_16x16x32_bf16 v[76:79], v[136:139], v[144:147], v[76:79]
	v_mfma_f32_16x16x32_bf16 v[104:107], v[128:131], v[152:155], v[104:107]
	v_mfma_f32_16x16x32_bf16 v[72:75], v[136:139], v[152:155], v[72:75]
	v_mfma_f32_16x16x32_bf16 v[100:103], v[128:131], v[160:163], v[100:103]
	v_mfma_f32_16x16x32_bf16 v[68:71], v[136:139], v[160:163], v[68:71]
	v_mfma_f32_16x16x32_bf16 v[96:99], v[128:131], v[178:181], v[96:99]
	v_mfma_f32_16x16x32_bf16 v[64:67], v[136:139], v[178:181], v[64:67]
	v_mfma_f32_16x16x32_bf16 v[108:111], v[132:135], v[148:151], v[108:111]
	v_mfma_f32_16x16x32_bf16 v[76:79], v[140:143], v[148:151], v[76:79]
	v_mfma_f32_16x16x32_bf16 v[104:107], v[132:135], v[156:159], v[104:107]
	v_mfma_f32_16x16x32_bf16 v[72:75], v[140:143], v[156:159], v[72:75]
	v_mfma_f32_16x16x32_bf16 v[100:103], v[132:135], v[174:177], v[100:103]
	v_mfma_f32_16x16x32_bf16 v[68:71], v[140:143], v[174:177], v[68:71]
	v_mfma_f32_16x16x32_bf16 v[96:99], v[132:135], v[182:185], v[96:99]
	v_mfma_f32_16x16x32_bf16 v[64:67], v[140:143], v[182:185], v[64:67]
	s_barrier
	s_add_u32 s4, s8, 0x160080
	s_addc_u32 s5, s9, 0
	s_add_i32 s8, s10, s21
	v_lshl_add_u64 v[128:129], s[4:5], 0, v[164:165]
	s_mov_b32 m0, s8
	s_nop 0
	global_load_lds_dwordx4 v[128:129], off
	v_lshl_add_u64 v[128:129], s[4:5], 0, v[166:167]
	s_add_i32 m0, s8, 0x2000
	s_nop 0
	global_load_lds_dwordx4 v[128:129], off
	s_waitcnt vmcnt(6)
	s_barrier
	v_mfma_f32_16x16x32_bf16 v[44:47], v[186:189], v[144:147], v[44:47]
	v_mfma_f32_16x16x32_bf16 v[12:15], v[194:197], v[144:147], v[12:15]
	v_mfma_f32_16x16x32_bf16 v[40:43], v[186:189], v[152:155], v[40:43]
	v_mfma_f32_16x16x32_bf16 v[8:11], v[194:197], v[152:155], v[8:11]
	v_mfma_f32_16x16x32_bf16 v[36:39], v[186:189], v[160:163], v[36:39]
	v_mfma_f32_16x16x32_bf16 v[4:7], v[194:197], v[160:163], v[4:7]
	v_mfma_f32_16x16x32_bf16 v[32:35], v[186:189], v[178:181], v[32:35]
	v_mfma_f32_16x16x32_bf16 v[0:3], v[194:197], v[178:181], v[0:3]
	v_mfma_f32_16x16x32_bf16 v[44:47], v[190:193], v[148:151], v[44:47]
	v_mfma_f32_16x16x32_bf16 v[12:15], v[202:205], v[148:151], v[12:15]
	v_mfma_f32_16x16x32_bf16 v[40:43], v[190:193], v[156:159], v[40:43]
	v_mfma_f32_16x16x32_bf16 v[8:11], v[202:205], v[156:159], v[8:11]
	v_mfma_f32_16x16x32_bf16 v[36:39], v[190:193], v[174:177], v[36:39]
	v_mfma_f32_16x16x32_bf16 v[4:7], v[202:205], v[174:177], v[4:7]
	v_mfma_f32_16x16x32_bf16 v[32:35], v[190:193], v[182:185], v[32:35]
	v_mfma_f32_16x16x32_bf16 v[0:3], v[202:205], v[182:185], v[0:3]
	s_add_i32 s16, s16, 2
	s_add_u32 s14, s14, 0x100
	s_addc_u32 s15, s15, 0
	s_cmpk_gt_u32 s16, 0x55
	s_mov_b64 s[4:5], s[6:7]
	s_barrier
	s_cbranch_scc0 .LBB0_3113
	s_lshl_b32 s8, s13, 21
	s_lshl_b32 s9, s12, 10
	s_lshr_b32 s16, s13, 4
	s_add_u32 s8, s8, s9
	s_mul_i32 s16, s16, 6
	s_add_i32 s16, s16, 35
	s_lshl_b32 s16, s16, 13
	s_add_u32 s16, s16, s9
	s_add_u32 s10, s26, s16
	s_addc_u32 s11, s27, 0
	s_add_u32 s6, s24, s8
	s_addc_u32 s7, s25, 0
	v_lshrrev_b32_e32 v224, 6, v206
	v_and_b32_e32 v225, 3, v224
	v_lshrrev_b32_e32 v224, 2, v224
	v_and_b32_e32 v205, 15, v206
	v_bfe_u32 v226, v206, 4, 2
	v_lshl_add_u32 v225, v225, 3, v226
	v_lshl_add_u32 v224, v224, 6, v205
	v_lshlrev_b32_e32 v205, 4, v225
	v_lshl_add_u32 v203, v224, 13, v205
	v_mov_b32_e32 v204, v203
	global_load_dwordx4 v[128:131], v205, s[10:11] offset:0
	global_load_dwordx4 v[132:135], v205, s[10:11] offset:64
	global_load_dwordx4 v[136:139], v205, s[10:11] offset:512
	global_load_dwordx4 v[140:143], v205, s[10:11] offset:576
	global_load_dwordx4 v[144:147], v203, s[6:7] offset:0
	global_load_dwordx4 v[148:151], v203, s[6:7] offset:64
	global_load_dwordx4 v[152:155], v203, s[6:7] offset:512
	global_load_dwordx4 v[156:159], v203, s[6:7] offset:576
	v_add_u32_e32 v203, 0x20000, v203
	global_load_dwordx4 v[160:163], v203, s[6:7] offset:0
	global_load_dwordx4 v[174:177], v203, s[6:7] offset:64
	global_load_dwordx4 v[178:181], v203, s[6:7] offset:512
	global_load_dwordx4 v[182:185], v203, s[6:7] offset:576
	v_add_u32_e32 v203, 0x20000, v203
	global_load_dwordx4 v[186:189], v203, s[6:7] offset:0
	global_load_dwordx4 v[190:193], v203, s[6:7] offset:64
	global_load_dwordx4 v[194:197], v203, s[6:7] offset:512
	global_load_dwordx4 v[208:211], v203, s[6:7] offset:576
	v_add_u32_e32 v203, 0x20000, v203
	global_load_dwordx4 v[212:215], v203, s[6:7] offset:0
	global_load_dwordx4 v[216:219], v203, s[6:7] offset:64
	global_load_dwordx4 v[220:223], v203, s[6:7] offset:512
	global_load_dwordx4 v[224:227], v203, s[6:7] offset:576
	v_add_u32_e32 v203, 0xa0000, v203
	s_waitcnt vmcnt(12)
	v_pk_fma_f32 v[124:125], v[124:125], v[128:129], v[144:145]
	v_pk_fma_f32 v[126:127], v[126:127], v[130:131], v[146:147]
	v_pk_fma_f32 v[92:93], v[92:93], v[132:133], v[148:149]
	v_pk_fma_f32 v[94:95], v[94:95], v[134:135], v[150:151]
	v_pk_fma_f32 v[60:61], v[60:61], v[136:137], v[152:153]
	v_pk_fma_f32 v[62:63], v[62:63], v[138:139], v[154:155]
	v_pk_fma_f32 v[28:29], v[28:29], v[140:141], v[156:157]
	v_pk_fma_f32 v[30:31], v[30:31], v[142:143], v[158:159]
	global_store_dwordx4 v204, v[124:127], s[6:7] offset:0
	global_store_dwordx4 v204, v[92:95], s[6:7] offset:64
	global_store_dwordx4 v204, v[60:63], s[6:7] offset:512
	global_store_dwordx4 v204, v[28:31], s[6:7] offset:576
	v_add_u32_e32 v204, 0x20000, v204
	global_load_dwordx4 v[144:147], v203, s[6:7] offset:0
	global_load_dwordx4 v[148:151], v203, s[6:7] offset:64
	global_load_dwordx4 v[152:155], v203, s[6:7] offset:512
	global_load_dwordx4 v[156:159], v203, s[6:7] offset:576
	v_add_u32_e32 v203, 0x20000, v203
	s_waitcnt vmcnt(16)
; DI void epi_resid(const Acc& acc, const P& p, int brow, int bcol, int layer, int gch, bool from_input) {
;     ...
;             for (int ai = 0; ai < 2; ++ai)
; #pragma unroll
;                 for (int m = 0; m < 4; ++m) {
;                     const int r = brow + ai * 128 + wr * 64 + m * 16 + fr;
;                     *(f32x4*)(xrow(p, r) + c0) = xv[ai][m] + g * acc[ai][bj][m][n];
;                 }
	v_pk_fma_f32 v[120:121], v[120:121], v[128:129], v[160:161]
	v_pk_fma_f32 v[122:123], v[122:123], v[130:131], v[162:163]
	v_pk_fma_f32 v[88:89], v[88:89], v[132:133], v[174:175]
	v_pk_fma_f32 v[90:91], v[90:91], v[134:135], v[176:177]
	v_pk_fma_f32 v[56:57], v[56:57], v[136:137], v[178:179]
	v_pk_fma_f32 v[58:59], v[58:59], v[138:139], v[180:181]
	v_pk_fma_f32 v[24:25], v[24:25], v[140:141], v[182:183]
	v_pk_fma_f32 v[26:27], v[26:27], v[142:143], v[184:185]
	global_store_dwordx4 v204, v[120:123], s[6:7] offset:0
	global_store_dwordx4 v204, v[88:91], s[6:7] offset:64
	global_store_dwordx4 v204, v[56:59], s[6:7] offset:512
	global_store_dwordx4 v204, v[24:27], s[6:7] offset:576
	v_add_u32_e32 v204, 0x20000, v204
	global_load_dwordx4 v[160:163], v203, s[6:7] offset:0
	global_load_dwordx4 v[174:177], v203, s[6:7] offset:64
	global_load_dwordx4 v[178:181], v203, s[6:7] offset:512
	global_load_dwordx4 v[182:185], v203, s[6:7] offset:576
	v_add_u32_e32 v203, 0x20000, v203
	s_waitcnt vmcnt(20)
	v_pk_fma_f32 v[116:117], v[116:117], v[128:129], v[186:187]
	v_pk_fma_f32 v[118:119], v[118:119], v[130:131], v[188:189]
	v_pk_fma_f32 v[84:85], v[84:85], v[132:133], v[190:191]
	v_pk_fma_f32 v[86:87], v[86:87], v[134:135], v[192:193]
	v_pk_fma_f32 v[52:53], v[52:53], v[136:137], v[194:195]
	v_pk_fma_f32 v[54:55], v[54:55], v[138:139], v[196:197]
	v_pk_fma_f32 v[20:21], v[20:21], v[140:141], v[208:209]
	v_pk_fma_f32 v[22:23], v[22:23], v[142:143], v[210:211]
	global_store_dwordx4 v204, v[116:119], s[6:7] offset:0
	global_store_dwordx4 v204, v[84:87], s[6:7] offset:64
	global_store_dwordx4 v204, v[52:55], s[6:7] offset:512
	global_store_dwordx4 v204, v[20:23], s[6:7] offset:576
	v_add_u32_e32 v204, 0x20000, v204
	global_load_dwordx4 v[186:189], v203, s[6:7] offset:0
	global_load_dwordx4 v[190:193], v203, s[6:7] offset:64
	global_load_dwordx4 v[194:197], v203, s[6:7] offset:512
	global_load_dwordx4 v[208:211], v203, s[6:7] offset:576
	v_add_u32_e32 v203, 0x20000, v203
	s_waitcnt vmcnt(24)
	v_pk_fma_f32 v[112:113], v[112:113], v[128:129], v[212:213]
	v_pk_fma_f32 v[114:115], v[114:115], v[130:131], v[214:215]
	v_pk_fma_f32 v[80:81], v[80:81], v[132:133], v[216:217]
	v_pk_fma_f32 v[82:83], v[82:83], v[134:135], v[218:219]
	v_pk_fma_f32 v[48:49], v[48:49], v[136:137], v[220:221]
	v_pk_fma_f32 v[50:51], v[50:51], v[138:139], v[222:223]
	v_pk_fma_f32 v[16:17], v[16:17], v[140:141], v[224:225]
	v_pk_fma_f32 v[18:19], v[18:19], v[142:143], v[226:227]
	global_store_dwordx4 v204, v[112:115], s[6:7] offset:0
	global_store_dwordx4 v204, v[80:83], s[6:7] offset:64
	global_store_dwordx4 v204, v[48:51], s[6:7] offset:512
	global_store_dwordx4 v204, v[16:19], s[6:7] offset:576
	v_add_u32_e32 v204, 0xa0000, v204
	global_load_dwordx4 v[212:215], v203, s[6:7] offset:0
	global_load_dwordx4 v[216:219], v203, s[6:7] offset:64
	global_load_dwordx4 v[220:223], v203, s[6:7] offset:512
	global_load_dwordx4 v[224:227], v203, s[6:7] offset:576
	s_waitcnt vmcnt(24)
	v_pk_fma_f32 v[108:109], v[108:109], v[128:129], v[144:145]
	v_pk_fma_f32 v[110:111], v[110:111], v[130:131], v[146:147]
	v_pk_fma_f32 v[76:77], v[76:77], v[132:133], v[148:149]
	v_pk_fma_f32 v[78:79], v[78:79], v[134:135], v[150:151]
	v_pk_fma_f32 v[44:45], v[44:45], v[136:137], v[152:153]
	v_pk_fma_f32 v[46:47], v[46:47], v[138:139], v[154:155]
	v_pk_fma_f32 v[12:13], v[12:13], v[140:141], v[156:157]
	v_pk_fma_f32 v[14:15], v[14:15], v[142:143], v[158:159]
	global_store_dwordx4 v204, v[108:111], s[6:7] offset:0
	global_store_dwordx4 v204, v[76:79], s[6:7] offset:64
	global_store_dwordx4 v204, v[44:47], s[6:7] offset:512
	global_store_dwordx4 v204, v[12:15], s[6:7] offset:576
	v_add_u32_e32 v204, 0x20000, v204
	s_waitcnt vmcnt(20)
	v_pk_fma_f32 v[104:105], v[104:105], v[128:129], v[160:161]
	v_pk_fma_f32 v[106:107], v[106:107], v[130:131], v[162:163]
	v_pk_fma_f32 v[72:73], v[72:73], v[132:133], v[174:175]
	v_pk_fma_f32 v[74:75], v[74:75], v[134:135], v[176:177]
	v_pk_fma_f32 v[40:41], v[40:41], v[136:137], v[178:179]
	v_pk_fma_f32 v[42:43], v[42:43], v[138:139], v[180:181]
	v_pk_fma_f32 v[8:9], v[8:9], v[140:141], v[182:183]
	v_pk_fma_f32 v[10:11], v[10:11], v[142:143], v[184:185]
	global_store_dwordx4 v204, v[104:107], s[6:7] offset:0
	global_store_dwordx4 v204, v[72:75], s[6:7] offset:64
	global_store_dwordx4 v204, v[40:43], s[6:7] offset:512
	global_store_dwordx4 v204, v[8:11], s[6:7] offset:576
	v_add_u32_e32 v204, 0x20000, v204
	s_waitcnt vmcnt(16)
	v_pk_fma_f32 v[100:101], v[100:101], v[128:129], v[186:187]
	v_pk_fma_f32 v[102:103], v[102:103], v[130:131], v[188:189]
	v_pk_fma_f32 v[68:69], v[68:69], v[132:133], v[190:191]
	v_pk_fma_f32 v[70:71], v[70:71], v[134:135], v[192:193]
	v_pk_fma_f32 v[36:37], v[36:37], v[136:137], v[194:195]
	v_pk_fma_f32 v[38:39], v[38:39], v[138:139], v[196:197]
	v_pk_fma_f32 v[4:5], v[4:5], v[140:141], v[208:209]
	v_pk_fma_f32 v[6:7], v[6:7], v[142:143], v[210:211]
	global_store_dwordx4 v204, v[100:103], s[6:7] offset:0
	global_store_dwordx4 v204, v[68:71], s[6:7] offset:64
	global_store_dwordx4 v204, v[36:39], s[6:7] offset:512
	global_store_dwordx4 v204, v[4:7], s[6:7] offset:576
	v_add_u32_e32 v204, 0x20000, v204
	s_waitcnt vmcnt(12)
	v_pk_fma_f32 v[96:97], v[96:97], v[128:129], v[212:213]
	v_pk_fma_f32 v[98:99], v[98:99], v[130:131], v[214:215]
	v_pk_fma_f32 v[64:65], v[64:65], v[132:133], v[216:217]
	v_pk_fma_f32 v[66:67], v[66:67], v[134:135], v[218:219]
	v_pk_fma_f32 v[32:33], v[32:33], v[136:137], v[220:221]
	v_pk_fma_f32 v[34:35], v[34:35], v[138:139], v[222:223]
	v_pk_fma_f32 v[0:1], v[0:1], v[140:141], v[224:225]
	v_pk_fma_f32 v[2:3], v[2:3], v[142:143], v[226:227]
	global_store_dwordx4 v204, v[96:99], s[6:7] offset:0
	global_store_dwordx4 v204, v[64:67], s[6:7] offset:64
	global_store_dwordx4 v204, v[32:35], s[6:7] offset:512
	global_store_dwordx4 v204, v[0:3], s[6:7] offset:576
	s_branch .Lresid_latch_ffndL1
